# P2 main-path epilogue batched; MFMAs of the all-padding half of the sample row tile skipped (pm==128) in all 7 GEMM loops
# baseline (speedup 1.0000x reference)
; #define PG8_STAGE(bufoff, gbase, voff) do { _Pragma("unroll") for (int _i = 0; _i < 2; ++_i) \
;         __builtin_amdgcn_global_load_lds((const unsigned*)((const char*)(gbase) + (voff)[_i]), (PG8_LAS unsigned*)(lds + (bufoff) + ldsw + _i * 8192), 16, 0, 0); } while (0)
; #define PG8_LDA(dst, b, h) do { _Pragma("unroll") for (int m = 0; m < 4; ++m) _Pragma("unroll") for (int k = 0; k < 2; ++k) dst[m][k] = *(const PG8_LAS bf16x8*)(lds + PG8_SA(b, h) + aoff + m * 2048 + k * 1024); } while (0)
; #define PG8_LDB(dst, b, h) do { _Pragma("unroll") for (int n = 0; n < 2; ++n) _Pragma("unroll") for (int k = 0; k < 2; ++k) dst[n][k] = *(const PG8_LAS bf16x8*)(lds + PG8_SB(b, h) + boff + n * 2048 + k * 1024); } while (0)
; #define PG8_MMA(ai, bj, At, Bt) do { __builtin_amdgcn_s_setprio(1); _Pragma("unroll") for (int m = 0; m < 4; ++m) _Pragma("unroll") for (int n = 0; n < 2; ++n) _Pragma("unroll") for (int k = 0; k < 2; ++k) \
;         acc[ai][bj][m][n] = __builtin_amdgcn_mfma_f32_16x16x32_bf16(Bt[n][k], At[m][k], acc[ai][bj][m][n], 0, 0, 0); __builtin_amdgcn_s_setprio(0); } while (0)
; #define PG8_WAIT_V(n) asm volatile("s_waitcnt vmcnt(" #n ")" ::: "memory")
; #define PG8_WAIT_L(n) asm volatile("s_waitcnt lgkmcnt(" #n ")" ::: "memory")
; #define PG8_BAR __builtin_amdgcn_s_barrier()
; #define PG8_SCHED __builtin_amdgcn_sched_barrier(0)
; template <class Epi, class Sched, bool ALIGN_EPI = false, bool SP2 = false, class Bg = BgNone>
; __device__ __forceinline__ void gemm_phase(PG8_LAS unsigned char* lds, const Gemm g, const Sched& S, const Epi& E, const int wave_sg, const Bg& bg = Bg()) {
;     ...
;             if (bg_on) { PG8_WAIT_V(10); } else { PG8_WAIT_V(8); } PG8_WAIT_L(0); PG8_BAR; PG8_MMA(1, 0, At, B0); PG8_MMA(1, 1, At, B1); PG8_BAR; PG8_SCHED;
;             PG8_LDB(B0, 1, 0); PG8_LDB(B1, 1, 1); PG8_SCHED; PG8_LDA(At, 1, 0); PG8_STAGE(PG8_SA(0, 1), a2 + hstep, voffA);
;             PG8_WAIT_V(8); PG8_WAIT_L(0); PG8_BAR; PG8_MMA(0, 0, At, B0); PG8_MMA(0, 1, At, B1); PG8_BAR; PG8_SCHED;
.LBB0_245:
	s_waitcnt lgkmcnt(0)
	s_barrier
	s_setprio 1
	s_waitcnt lgkmcnt(0)
	s_cmpk_eq_u32 s44, 0x80
	s_cbranch_scc1 .Lskiphalf_0
	v_mfma_f32_16x16x32_bf16 v[62:65], v[150:153], v[190:193], v[62:65]
	v_mfma_f32_16x16x32_bf16 v[58:61], v[158:161], v[190:193], v[58:61]
	v_mfma_f32_16x16x32_bf16 v[46:49], v[150:153], v[182:185], v[46:49]
	v_mfma_f32_16x16x32_bf16 v[42:45], v[158:161], v[182:185], v[42:45]
	v_mfma_f32_16x16x32_bf16 v[30:33], v[150:153], v[174:177], v[30:33]
	v_mfma_f32_16x16x32_bf16 v[26:29], v[158:161], v[174:177], v[26:29]
	v_mfma_f32_16x16x32_bf16 v[14:17], v[150:153], v[166:169], v[14:17]
	v_mfma_f32_16x16x32_bf16 v[10:13], v[158:161], v[166:169], v[10:13]
	v_mfma_f32_16x16x32_bf16 v[62:65], v[154:157], v[194:197], v[62:65]
	v_mfma_f32_16x16x32_bf16 v[58:61], v[162:165], v[194:197], v[58:61]
	v_mfma_f32_16x16x32_bf16 v[46:49], v[154:157], v[186:189], v[46:49]
	v_mfma_f32_16x16x32_bf16 v[42:45], v[162:165], v[186:189], v[42:45]
	v_mfma_f32_16x16x32_bf16 v[30:33], v[154:157], v[178:181], v[30:33]
	v_mfma_f32_16x16x32_bf16 v[26:29], v[162:165], v[178:181], v[26:29]
	v_mfma_f32_16x16x32_bf16 v[14:17], v[154:157], v[170:173], v[14:17]
	v_mfma_f32_16x16x32_bf16 v[10:13], v[162:165], v[170:173], v[10:13]
	s_setprio 0
	s_setprio 1
	v_mfma_f32_16x16x32_bf16 v[66:69], v[134:137], v[190:193], v[66:69]
	v_mfma_f32_16x16x32_bf16 v[54:57], v[142:145], v[190:193], v[54:57]
	v_mfma_f32_16x16x32_bf16 v[50:53], v[134:137], v[182:185], v[50:53]
	v_mfma_f32_16x16x32_bf16 v[38:41], v[142:145], v[182:185], v[38:41]
	v_mfma_f32_16x16x32_bf16 v[34:37], v[134:137], v[174:177], v[34:37]
	v_mfma_f32_16x16x32_bf16 v[22:25], v[142:145], v[174:177], v[22:25]
	v_mfma_f32_16x16x32_bf16 v[18:21], v[134:137], v[166:169], v[18:21]
	v_mfma_f32_16x16x32_bf16 v[6:9], v[142:145], v[166:169], v[6:9]
	v_mfma_f32_16x16x32_bf16 v[66:69], v[138:141], v[194:197], v[66:69]
	v_mfma_f32_16x16x32_bf16 v[54:57], v[146:149], v[194:197], v[54:57]
	v_mfma_f32_16x16x32_bf16 v[50:53], v[138:141], v[186:189], v[50:53]
	v_mfma_f32_16x16x32_bf16 v[38:41], v[146:149], v[186:189], v[38:41]
	v_mfma_f32_16x16x32_bf16 v[34:37], v[138:141], v[178:181], v[34:37]
	v_mfma_f32_16x16x32_bf16 v[22:25], v[146:149], v[178:181], v[22:25]
	v_mfma_f32_16x16x32_bf16 v[18:21], v[138:141], v[170:173], v[18:21]
	v_mfma_f32_16x16x32_bf16 v[6:9], v[146:149], v[170:173], v[6:9]
.Lskiphalf_0:
	s_setprio 0
	s_barrier
	s_add_i32 s56, 0, 0x18000
	v_add_u32_e32 v0, s56, v234
	s_add_i32 s57, 0, 0x1c000
	ds_read_b128 v[134:137], v0
	ds_read_b128 v[138:141], v0 offset:1024
	ds_read_b128 v[142:145], v0 offset:2048
	ds_read_b128 v[146:149], v0 offset:3072
	v_add_u32_e32 v0, s57, v234
	ds_read_b128 v[150:153], v0
	ds_read_b128 v[154:157], v0 offset:1024
	ds_read_b128 v[158:161], v0 offset:2048
	ds_read_b128 v[162:165], v0 offset:3072
	s_add_u32 s54, s54, 0x40000
	s_addc_u32 s55, s55, 0
	s_mov_b32 m0, s63
	v_lshl_add_u64 v[240:241], s[54:55], 0, v[198:199]
	ds_read_b128 v[166:169], v238 offset:32768
	ds_read_b128 v[170:173], v238 offset:33792
	ds_read_b128 v[174:177], v238 offset:34816
	ds_read_b128 v[178:181], v238 offset:35840
	ds_read_b128 v[182:185], v238 offset:36864
	ds_read_b128 v[186:189], v238 offset:37888
	ds_read_b128 v[190:193], v238 offset:38912
	ds_read_b128 v[194:197], v238 offset:39936
	global_load_lds_dwordx4 v[240:241], off
	v_lshl_add_u64 v[240:241], s[54:55], 0, v[202:203]
	s_mov_b32 m0, s64
	s_nop 0
	global_load_lds_dwordx4 v[240:241], off
	s_waitcnt vmcnt(8)
	s_waitcnt lgkmcnt(0)
	s_barrier
	s_setprio 1
	s_waitcnt lgkmcnt(0)
	v_mfma_f32_16x16x32_bf16 v[126:129], v[134:137], v[166:169], v[126:129]
	v_mfma_f32_16x16x32_bf16 v[122:125], v[142:145], v[166:169], v[122:125]
	v_mfma_f32_16x16x32_bf16 v[110:113], v[134:137], v[174:177], v[110:113]
	v_mfma_f32_16x16x32_bf16 v[106:109], v[142:145], v[174:177], v[106:109]
	v_mfma_f32_16x16x32_bf16 v[94:97], v[134:137], v[182:185], v[94:97]
	v_mfma_f32_16x16x32_bf16 v[90:93], v[142:145], v[182:185], v[90:93]
	v_mfma_f32_16x16x32_bf16 v[78:81], v[134:137], v[190:193], v[78:81]
	v_mfma_f32_16x16x32_bf16 v[74:77], v[142:145], v[190:193], v[74:77]
	v_mfma_f32_16x16x32_bf16 v[126:129], v[138:141], v[170:173], v[126:129]
	v_mfma_f32_16x16x32_bf16 v[122:125], v[146:149], v[170:173], v[122:125]
	v_mfma_f32_16x16x32_bf16 v[110:113], v[138:141], v[178:181], v[110:113]
	v_mfma_f32_16x16x32_bf16 v[106:109], v[146:149], v[178:181], v[106:109]
	v_mfma_f32_16x16x32_bf16 v[94:97], v[138:141], v[186:189], v[94:97]
	v_mfma_f32_16x16x32_bf16 v[90:93], v[146:149], v[186:189], v[90:93]
	v_mfma_f32_16x16x32_bf16 v[78:81], v[138:141], v[194:197], v[78:81]
	v_mfma_f32_16x16x32_bf16 v[74:77], v[146:149], v[194:197], v[74:77]
	s_setprio 0
	s_setprio 1
	v_mfma_f32_16x16x32_bf16 v[130:133], v[150:153], v[166:169], v[130:133]
	v_mfma_f32_16x16x32_bf16 v[118:121], v[158:161], v[166:169], v[118:121]
	v_mfma_f32_16x16x32_bf16 v[114:117], v[150:153], v[174:177], v[114:117]
	v_mfma_f32_16x16x32_bf16 v[102:105], v[158:161], v[174:177], v[102:105]
	v_mfma_f32_16x16x32_bf16 v[98:101], v[150:153], v[182:185], v[98:101]
	v_mfma_f32_16x16x32_bf16 v[86:89], v[158:161], v[182:185], v[86:89]
	v_mfma_f32_16x16x32_bf16 v[82:85], v[150:153], v[190:193], v[82:85]
	v_mfma_f32_16x16x32_bf16 v[70:73], v[158:161], v[190:193], v[70:73]
	v_mfma_f32_16x16x32_bf16 v[130:133], v[154:157], v[170:173], v[130:133]
	v_mfma_f32_16x16x32_bf16 v[118:121], v[162:165], v[170:173], v[118:121]
	v_mfma_f32_16x16x32_bf16 v[114:117], v[154:157], v[178:181], v[114:117]
	v_mfma_f32_16x16x32_bf16 v[102:105], v[162:165], v[178:181], v[102:105]
	v_mfma_f32_16x16x32_bf16 v[98:101], v[154:157], v[186:189], v[98:101]
	v_mfma_f32_16x16x32_bf16 v[86:89], v[162:165], v[186:189], v[86:89]
	v_mfma_f32_16x16x32_bf16 v[82:85], v[154:157], v[194:197], v[82:85]
	v_mfma_f32_16x16x32_bf16 v[70:73], v[162:165], v[194:197], v[70:73]
	s_setprio 0
	s_barrier
; #define PG8_STAGE(bufoff, gbase, voff) do { _Pragma("unroll") for (int _i = 0; _i < 2; ++_i) \
;         __builtin_amdgcn_global_load_lds((const unsigned*)((const char*)(gbase) + (voff)[_i]), (PG8_LAS unsigned*)(lds + (bufoff) + ldsw + _i * 8192), 16, 0, 0); } while (0)
; #define PG8_LDA(dst, b, h) do { _Pragma("unroll") for (int m = 0; m < 4; ++m) _Pragma("unroll") for (int k = 0; k < 2; ++k) dst[m][k] = *(const PG8_LAS bf16x8*)(lds + PG8_SA(b, h) + aoff + m * 2048 + k * 1024); } while (0)
; #define PG8_MMA(ai, bj, At, Bt) do { __builtin_amdgcn_s_setprio(1); _Pragma("unroll") for (int m = 0; m < 4; ++m) _Pragma("unroll") for (int n = 0; n < 2; ++n) _Pragma("unroll") for (int k = 0; k < 2; ++k) \
;         acc[ai][bj][m][n] = __builtin_amdgcn_mfma_f32_16x16x32_bf16(Bt[n][k], At[m][k], acc[ai][bj][m][n], 0, 0, 0); __builtin_amdgcn_s_setprio(0); } while (0)
; #define PG8_WAIT_V(n) asm volatile("s_waitcnt vmcnt(" #n ")" ::: "memory")
; #define PG8_WAIT_L(n) asm volatile("s_waitcnt lgkmcnt(" #n ")" ::: "memory")
; #define PG8_BAR __builtin_amdgcn_s_barrier()
; #define PG8_SCHED __builtin_amdgcn_sched_barrier(0)
; template <class Epi, class Sched, bool ALIGN_EPI = false, bool SP2 = false, class Bg = BgNone>
; __device__ __forceinline__ void gemm_phase(PG8_LAS unsigned char* lds, const Gemm g, const Sched& S, const Epi& E, const int wave_sg, const Bg& bg = Bg()) {
;     ...
;             PG8_LDA(At, 1, 1); PG8_STAGE(PG8_SB(1, 0), b3, voffB); PG8_STAGE(PG8_SB(1, 1), b3 + hstep, voffB); PG8_STAGE(PG8_SA(1, 0), a3, voffA);
;             PG8_WAIT_V(8); PG8_WAIT_L(0); PG8_BAR; PG8_MMA(1, 0, At, B0); PG8_MMA(1, 1, At, B1); PG8_BAR; PG8_SCHED;
	s_add_i32 s54, s56, s58
	v_lshl_add_u64 v[230:231], v[230:231], 0, s[26:27]
	s_mov_b32 m0, s54
	ds_read_b128 v[166:169], v238 offset:49152
	ds_read_b128 v[170:173], v238 offset:50176
	ds_read_b128 v[174:177], v238 offset:51200
	ds_read_b128 v[178:181], v238 offset:52224
	ds_read_b128 v[182:185], v238 offset:53248
	ds_read_b128 v[186:189], v238 offset:54272
	ds_read_b128 v[190:193], v238 offset:55296
	ds_read_b128 v[194:197], v238 offset:56320
	global_load_lds_dwordx4 v[230:231], off
	s_add_i32 m0, s54, 0x2000
	s_add_u32 s52, s52, 0x40080
	v_lshl_add_u64 v[228:229], v[228:229], 0, s[26:27]
	s_addc_u32 s53, s53, 0
	s_add_i32 s54, s57, s58
	global_load_lds_dwordx4 v[228:229], off
	v_lshl_add_u64 v[228:229], s[52:53], 0, v[200:201]
	s_mov_b32 m0, s54
	v_lshl_add_u64 v[224:225], v[224:225], 0, s[26:27]
	global_load_lds_dwordx4 v[228:229], off
	v_lshl_add_u64 v[228:229], s[52:53], 0, v[204:205]
	s_add_i32 m0, s54, 0x2000
	s_nop 0
	global_load_lds_dwordx4 v[228:229], off
	s_mov_b32 m0, s65
	s_nop 0
	global_load_lds_dwordx4 v[224:225], off
	v_lshl_add_u64 v[224:225], v[226:227], 0, s[26:27]
	s_mov_b32 m0, s66
	s_nop 0
	global_load_lds_dwordx4 v[224:225], off
	s_waitcnt vmcnt(8)
	s_waitcnt lgkmcnt(0)
	s_barrier
	s_setprio 1
	s_waitcnt lgkmcnt(0)
	s_cmpk_eq_u32 s44, 0x80
	s_cbranch_scc1 .Lskiphalf_1
	v_mfma_f32_16x16x32_bf16 v[62:65], v[134:137], v[166:169], v[62:65]
	v_mfma_f32_16x16x32_bf16 v[58:61], v[142:145], v[166:169], v[58:61]
	v_mfma_f32_16x16x32_bf16 v[46:49], v[134:137], v[174:177], v[46:49]
	v_mfma_f32_16x16x32_bf16 v[42:45], v[142:145], v[174:177], v[42:45]
	v_mfma_f32_16x16x32_bf16 v[30:33], v[134:137], v[182:185], v[30:33]
	v_mfma_f32_16x16x32_bf16 v[26:29], v[142:145], v[182:185], v[26:29]
	v_mfma_f32_16x16x32_bf16 v[14:17], v[134:137], v[190:193], v[14:17]
	v_mfma_f32_16x16x32_bf16 v[10:13], v[142:145], v[190:193], v[10:13]
	v_mfma_f32_16x16x32_bf16 v[62:65], v[138:141], v[170:173], v[62:65]
	v_mfma_f32_16x16x32_bf16 v[58:61], v[146:149], v[170:173], v[58:61]
	v_mfma_f32_16x16x32_bf16 v[46:49], v[138:141], v[178:181], v[46:49]
	v_mfma_f32_16x16x32_bf16 v[42:45], v[146:149], v[178:181], v[42:45]
	v_mfma_f32_16x16x32_bf16 v[30:33], v[138:141], v[186:189], v[30:33]
	v_mfma_f32_16x16x32_bf16 v[26:29], v[146:149], v[186:189], v[26:29]
	v_mfma_f32_16x16x32_bf16 v[14:17], v[138:141], v[194:197], v[14:17]
	v_mfma_f32_16x16x32_bf16 v[10:13], v[146:149], v[194:197], v[10:13]
	s_setprio 0
	s_setprio 1
	v_mfma_f32_16x16x32_bf16 v[66:69], v[150:153], v[166:169], v[66:69]
	v_mfma_f32_16x16x32_bf16 v[54:57], v[158:161], v[166:169], v[54:57]
	v_mfma_f32_16x16x32_bf16 v[50:53], v[150:153], v[174:177], v[50:53]
	v_mfma_f32_16x16x32_bf16 v[38:41], v[158:161], v[174:177], v[38:41]
	v_mfma_f32_16x16x32_bf16 v[34:37], v[150:153], v[182:185], v[34:37]
	v_mfma_f32_16x16x32_bf16 v[22:25], v[158:161], v[182:185], v[22:25]
	v_mfma_f32_16x16x32_bf16 v[18:21], v[150:153], v[190:193], v[18:21]
	v_mfma_f32_16x16x32_bf16 v[6:9], v[158:161], v[190:193], v[6:9]
	v_mfma_f32_16x16x32_bf16 v[66:69], v[154:157], v[170:173], v[66:69]
	v_mfma_f32_16x16x32_bf16 v[54:57], v[162:165], v[170:173], v[54:57]
	v_mfma_f32_16x16x32_bf16 v[50:53], v[154:157], v[178:181], v[50:53]
	v_mfma_f32_16x16x32_bf16 v[38:41], v[162:165], v[178:181], v[38:41]
	v_mfma_f32_16x16x32_bf16 v[34:37], v[154:157], v[186:189], v[34:37]
	v_mfma_f32_16x16x32_bf16 v[22:25], v[162:165], v[186:189], v[22:25]
	v_mfma_f32_16x16x32_bf16 v[18:21], v[154:157], v[194:197], v[18:21]
	v_mfma_f32_16x16x32_bf16 v[6:9], v[162:165], v[194:197], v[6:9]
.Lskiphalf_1:
	s_setprio 0
	s_barrier
	s_add_i32 s80, s80, 2
	s_add_u32 s50, s50, 0x100
	s_addc_u32 s51, s51, 0
	s_cmp_gt_u32 s80, 13
	v_add_u32_e32 v239, s71, v239
	s_cbranch_scc1 .LBB0_256

; #define PG8_STAGE(bufoff, gbase, voff) do { _Pragma("unroll") for (int _i = 0; _i < 2; ++_i) \
;         __builtin_amdgcn_global_load_lds((const unsigned*)((const char*)(gbase) + (voff)[_i]), (PG8_LAS unsigned*)(lds + (bufoff) + ldsw + _i * 8192), 16, 0, 0); } while (0)
; #define PG8_LDA(dst, b, h) do { _Pragma("unroll") for (int m = 0; m < 4; ++m) _Pragma("unroll") for (int k = 0; k < 2; ++k) dst[m][k] = *(const PG8_LAS bf16x8*)(lds + PG8_SA(b, h) + aoff + m * 2048 + k * 1024); } while (0)
; #define PG8_LDB(dst, b, h) do { _Pragma("unroll") for (int n = 0; n < 2; ++n) _Pragma("unroll") for (int k = 0; k < 2; ++k) dst[n][k] = *(const PG8_LAS bf16x8*)(lds + PG8_SB(b, h) + boff + n * 2048 + k * 1024); } while (0)
; #define PG8_MMA(ai, bj, At, Bt) do { __builtin_amdgcn_s_setprio(1); _Pragma("unroll") for (int m = 0; m < 4; ++m) _Pragma("unroll") for (int n = 0; n < 2; ++n) _Pragma("unroll") for (int k = 0; k < 2; ++k) \
;         acc[ai][bj][m][n] = __builtin_amdgcn_mfma_f32_16x16x32_bf16(Bt[n][k], At[m][k], acc[ai][bj][m][n], 0, 0, 0); __builtin_amdgcn_s_setprio(0); } while (0)
; #define PG8_WAIT_V(n) asm volatile("s_waitcnt vmcnt(" #n ")" ::: "memory")
; #define PG8_WAIT_L(n) asm volatile("s_waitcnt lgkmcnt(" #n ")" ::: "memory")
; #define PG8_BAR __builtin_amdgcn_s_barrier()
; #define PG8_SCHED __builtin_amdgcn_sched_barrier(0)
; template <class Epi, class Sched, bool ALIGN_EPI = false, bool SP2 = false, class Bg = BgNone>
; __device__ __forceinline__ void gemm_phase(PG8_LAS unsigned char* lds, const Gemm g, const Sched& S, const Epi& E, const int wave_sg, const Bg& bg = Bg()) {
;     ...
;             if (bg_on) { PG8_WAIT_V(10); } else { PG8_WAIT_V(8); } PG8_WAIT_L(0); PG8_BAR; PG8_MMA(1, 0, At, B0); PG8_MMA(1, 1, At, B1); PG8_BAR; PG8_SCHED;
;             PG8_LDB(B0, 1, 0); PG8_LDB(B1, 1, 1); PG8_SCHED; PG8_LDA(At, 1, 0); PG8_STAGE(PG8_SA(0, 1), a2 + hstep, voffA);
;             PG8_WAIT_V(8); PG8_WAIT_L(0); PG8_BAR; PG8_MMA(0, 0, At, B0); PG8_MMA(0, 1, At, B1); PG8_BAR; PG8_SCHED;
.LBB0_376:
	s_waitcnt lgkmcnt(0)
	s_add_i32 s70, s70, 2
	s_barrier
	s_setprio 1
	s_waitcnt lgkmcnt(0)
	s_cmpk_eq_u32 s94, 0x80
	s_cbranch_scc1 .Lskiphalf_2
	v_mfma_f32_16x16x32_bf16 v[130:133], v[150:153], v[190:193], v[130:133]
	v_mfma_f32_16x16x32_bf16 v[126:129], v[158:161], v[190:193], v[126:129]
	v_mfma_f32_16x16x32_bf16 v[114:117], v[150:153], v[182:185], v[114:117]
	v_mfma_f32_16x16x32_bf16 v[110:113], v[158:161], v[182:185], v[110:113]
	v_mfma_f32_16x16x32_bf16 v[98:101], v[150:153], v[174:177], v[98:101]
	v_mfma_f32_16x16x32_bf16 v[94:97], v[158:161], v[174:177], v[94:97]
	v_mfma_f32_16x16x32_bf16 v[82:85], v[150:153], v[166:169], v[82:85]
	v_mfma_f32_16x16x32_bf16 v[74:77], v[158:161], v[166:169], v[74:77]
	v_mfma_f32_16x16x32_bf16 v[130:133], v[154:157], v[194:197], v[130:133]
	v_mfma_f32_16x16x32_bf16 v[126:129], v[162:165], v[194:197], v[126:129]
	v_mfma_f32_16x16x32_bf16 v[114:117], v[154:157], v[186:189], v[114:117]
	v_mfma_f32_16x16x32_bf16 v[110:113], v[162:165], v[186:189], v[110:113]
	v_mfma_f32_16x16x32_bf16 v[98:101], v[154:157], v[178:181], v[98:101]
	v_mfma_f32_16x16x32_bf16 v[94:97], v[162:165], v[178:181], v[94:97]
	v_mfma_f32_16x16x32_bf16 v[82:85], v[154:157], v[170:173], v[82:85]
	v_mfma_f32_16x16x32_bf16 v[74:77], v[162:165], v[170:173], v[74:77]
	s_setprio 0
	s_setprio 1
	v_mfma_f32_16x16x32_bf16 v[122:125], v[134:137], v[190:193], v[122:125]
	v_mfma_f32_16x16x32_bf16 v[118:121], v[142:145], v[190:193], v[118:121]
	v_mfma_f32_16x16x32_bf16 v[106:109], v[134:137], v[182:185], v[106:109]
	v_mfma_f32_16x16x32_bf16 v[102:105], v[142:145], v[182:185], v[102:105]
	v_mfma_f32_16x16x32_bf16 v[90:93], v[134:137], v[174:177], v[90:93]
	v_mfma_f32_16x16x32_bf16 v[86:89], v[142:145], v[174:177], v[86:89]
	v_mfma_f32_16x16x32_bf16 v[66:69], v[134:137], v[166:169], v[66:69]
	v_mfma_f32_16x16x32_bf16 v[42:45], v[142:145], v[166:169], v[42:45]
	v_mfma_f32_16x16x32_bf16 v[122:125], v[138:141], v[194:197], v[122:125]
	v_mfma_f32_16x16x32_bf16 v[118:121], v[146:149], v[194:197], v[118:121]
	v_mfma_f32_16x16x32_bf16 v[106:109], v[138:141], v[186:189], v[106:109]
	v_mfma_f32_16x16x32_bf16 v[102:105], v[146:149], v[186:189], v[102:105]
	v_mfma_f32_16x16x32_bf16 v[90:93], v[138:141], v[178:181], v[90:93]
	v_mfma_f32_16x16x32_bf16 v[86:89], v[146:149], v[178:181], v[86:89]
	v_mfma_f32_16x16x32_bf16 v[66:69], v[138:141], v[170:173], v[66:69]
	v_mfma_f32_16x16x32_bf16 v[42:45], v[146:149], v[170:173], v[42:45]
.Lskiphalf_2:
	s_setprio 0
	s_barrier
	s_add_i32 s52, 0, 0x18000
	v_add_u32_e32 v0, s52, v231
	s_add_i32 s53, 0, 0x1c000
	ds_read_b128 v[134:137], v0
	ds_read_b128 v[138:141], v0 offset:1024
	ds_read_b128 v[142:145], v0 offset:2048
	ds_read_b128 v[146:149], v0 offset:3072
	v_add_u32_e32 v0, s53, v231
	ds_read_b128 v[150:153], v0
	ds_read_b128 v[154:157], v0 offset:1024
	ds_read_b128 v[158:161], v0 offset:2048
	ds_read_b128 v[162:165], v0 offset:3072
	s_add_u32 s50, s50, 0xb0000
	s_addc_u32 s51, s51, 0
	s_mov_b32 m0, s64
	v_lshl_add_u64 v[238:239], s[50:51], 0, v[198:199]
	ds_read_b128 v[166:169], v235 offset:32768
	ds_read_b128 v[170:173], v235 offset:33792
	ds_read_b128 v[174:177], v235 offset:34816
	ds_read_b128 v[178:181], v235 offset:35840
	ds_read_b128 v[182:185], v235 offset:36864
	ds_read_b128 v[186:189], v235 offset:37888
	ds_read_b128 v[190:193], v235 offset:38912
	ds_read_b128 v[194:197], v235 offset:39936
	global_load_lds_dwordx4 v[238:239], off
	v_lshl_add_u64 v[238:239], s[50:51], 0, v[200:201]
	s_mov_b32 m0, s65
	s_nop 0
	global_load_lds_dwordx4 v[238:239], off
	s_waitcnt vmcnt(8)
	s_waitcnt lgkmcnt(0)
	s_barrier
	s_setprio 1
	s_waitcnt lgkmcnt(0)
	v_mfma_f32_16x16x32_bf16 v[78:81], v[134:137], v[166:169], v[78:81]
	v_mfma_f32_16x16x32_bf16 v[70:73], v[142:145], v[166:169], v[70:73]
	v_mfma_f32_16x16x32_bf16 v[58:61], v[134:137], v[174:177], v[58:61]
	v_mfma_f32_16x16x32_bf16 v[50:53], v[142:145], v[174:177], v[50:53]
	v_mfma_f32_16x16x32_bf16 v[38:41], v[134:137], v[182:185], v[38:41]
	v_mfma_f32_16x16x32_bf16 v[30:33], v[142:145], v[182:185], v[30:33]
	v_mfma_f32_16x16x32_bf16 v[22:25], v[134:137], v[190:193], v[22:25]
	v_mfma_f32_16x16x32_bf16 v[14:17], v[142:145], v[190:193], v[14:17]
	v_mfma_f32_16x16x32_bf16 v[78:81], v[138:141], v[170:173], v[78:81]
	v_mfma_f32_16x16x32_bf16 v[70:73], v[146:149], v[170:173], v[70:73]
	v_mfma_f32_16x16x32_bf16 v[58:61], v[138:141], v[178:181], v[58:61]
	v_mfma_f32_16x16x32_bf16 v[50:53], v[146:149], v[178:181], v[50:53]
	v_mfma_f32_16x16x32_bf16 v[38:41], v[138:141], v[186:189], v[38:41]
	v_mfma_f32_16x16x32_bf16 v[30:33], v[146:149], v[186:189], v[30:33]
	v_mfma_f32_16x16x32_bf16 v[22:25], v[138:141], v[194:197], v[22:25]
	v_mfma_f32_16x16x32_bf16 v[14:17], v[146:149], v[194:197], v[14:17]
	s_setprio 0
	s_setprio 1
	v_mfma_f32_16x16x32_bf16 v[62:65], v[150:153], v[166:169], v[62:65]
	v_mfma_f32_16x16x32_bf16 v[54:57], v[158:161], v[166:169], v[54:57]
	v_mfma_f32_16x16x32_bf16 v[46:49], v[150:153], v[174:177], v[46:49]
	v_mfma_f32_16x16x32_bf16 v[34:37], v[158:161], v[174:177], v[34:37]
	v_mfma_f32_16x16x32_bf16 v[26:29], v[150:153], v[182:185], v[26:29]
	v_mfma_f32_16x16x32_bf16 v[18:21], v[158:161], v[182:185], v[18:21]
	v_mfma_f32_16x16x32_bf16 v[10:13], v[150:153], v[190:193], v[10:13]
	v_mfma_f32_16x16x32_bf16 v[6:9], v[158:161], v[190:193], v[6:9]
	v_mfma_f32_16x16x32_bf16 v[62:65], v[154:157], v[170:173], v[62:65]
	v_mfma_f32_16x16x32_bf16 v[54:57], v[162:165], v[170:173], v[54:57]
	v_mfma_f32_16x16x32_bf16 v[46:49], v[154:157], v[178:181], v[46:49]
	v_mfma_f32_16x16x32_bf16 v[34:37], v[162:165], v[178:181], v[34:37]
	v_mfma_f32_16x16x32_bf16 v[26:29], v[154:157], v[186:189], v[26:29]
	v_mfma_f32_16x16x32_bf16 v[18:21], v[162:165], v[186:189], v[18:21]
	v_mfma_f32_16x16x32_bf16 v[10:13], v[154:157], v[194:197], v[10:13]
	v_mfma_f32_16x16x32_bf16 v[6:9], v[162:165], v[194:197], v[6:9]
	s_setprio 0
	s_barrier
; #define PG8_STAGE(bufoff, gbase, voff) do { _Pragma("unroll") for (int _i = 0; _i < 2; ++_i) \
;         __builtin_amdgcn_global_load_lds((const unsigned*)((const char*)(gbase) + (voff)[_i]), (PG8_LAS unsigned*)(lds + (bufoff) + ldsw + _i * 8192), 16, 0, 0); } while (0)
; #define PG8_LDA(dst, b, h) do { _Pragma("unroll") for (int m = 0; m < 4; ++m) _Pragma("unroll") for (int k = 0; k < 2; ++k) dst[m][k] = *(const PG8_LAS bf16x8*)(lds + PG8_SA(b, h) + aoff + m * 2048 + k * 1024); } while (0)
; #define PG8_MMA(ai, bj, At, Bt) do { __builtin_amdgcn_s_setprio(1); _Pragma("unroll") for (int m = 0; m < 4; ++m) _Pragma("unroll") for (int n = 0; n < 2; ++n) _Pragma("unroll") for (int k = 0; k < 2; ++k) \
;         acc[ai][bj][m][n] = __builtin_amdgcn_mfma_f32_16x16x32_bf16(Bt[n][k], At[m][k], acc[ai][bj][m][n], 0, 0, 0); __builtin_amdgcn_s_setprio(0); } while (0)
; #define PG8_WAIT_V(n) asm volatile("s_waitcnt vmcnt(" #n ")" ::: "memory")
; #define PG8_WAIT_L(n) asm volatile("s_waitcnt lgkmcnt(" #n ")" ::: "memory")
; #define PG8_BAR __builtin_amdgcn_s_barrier()
; #define PG8_SCHED __builtin_amdgcn_sched_barrier(0)
; template <class Epi, class Sched, bool ALIGN_EPI = false, bool SP2 = false, class Bg = BgNone>
; __device__ __forceinline__ void gemm_phase(PG8_LAS unsigned char* lds, const Gemm g, const Sched& S, const Epi& E, const int wave_sg, const Bg& bg = Bg()) {
;     ...
;         for (int t = 0; t < cnt_; t += 2) {
;     ...
;             PG8_LDA(At, 1, 1); PG8_STAGE(PG8_SB(1, 0), b3, voffB); PG8_STAGE(PG8_SB(1, 1), b3 + hstep, voffB); PG8_STAGE(PG8_SA(1, 0), a3, voffA);
;             PG8_WAIT_V(8); PG8_WAIT_L(0); PG8_BAR; PG8_MMA(1, 0, At, B0); PG8_MMA(1, 1, At, B1); PG8_BAR; PG8_SCHED;
	s_add_i32 s50, s52, s57
	v_lshl_add_u64 v[228:229], v[228:229], 0, s[36:37]
	s_mov_b32 m0, s50
	ds_read_b128 v[166:169], v235 offset:49152
	ds_read_b128 v[170:173], v235 offset:50176
	ds_read_b128 v[174:177], v235 offset:51200
	ds_read_b128 v[178:181], v235 offset:52224
	ds_read_b128 v[182:185], v235 offset:53248
	ds_read_b128 v[186:189], v235 offset:54272
	ds_read_b128 v[190:193], v235 offset:55296
	ds_read_b128 v[194:197], v235 offset:56320
	global_load_lds_dwordx4 v[228:229], off
	s_add_i32 m0, s50, 0x2000
	s_add_u32 s48, s48, 0xb0080
	v_lshl_add_u64 v[226:227], v[226:227], 0, s[36:37]
	s_addc_u32 s49, s49, 0
	s_add_i32 s50, s53, s57
	global_load_lds_dwordx4 v[226:227], off
	v_lshl_add_u64 v[226:227], s[48:49], 0, v[198:199]
	s_mov_b32 m0, s50
	v_lshl_add_u64 v[222:223], v[222:223], 0, s[36:37]
	global_load_lds_dwordx4 v[226:227], off
	v_lshl_add_u64 v[226:227], s[48:49], 0, v[200:201]
	s_add_i32 m0, s50, 0x2000
	s_nop 0
	global_load_lds_dwordx4 v[226:227], off
	s_mov_b32 m0, s69
	s_nop 0
	global_load_lds_dwordx4 v[222:223], off
	v_lshl_add_u64 v[222:223], v[224:225], 0, s[36:37]
	s_mov_b32 m0, s71
	s_nop 0
	global_load_lds_dwordx4 v[222:223], off
	s_waitcnt vmcnt(8)
	s_waitcnt lgkmcnt(0)
	s_barrier
	s_setprio 1
	s_waitcnt lgkmcnt(0)
	s_cmpk_eq_u32 s94, 0x80
	s_cbranch_scc1 .Lskiphalf_3
	v_mfma_f32_16x16x32_bf16 v[130:133], v[134:137], v[166:169], v[130:133]
	v_mfma_f32_16x16x32_bf16 v[126:129], v[142:145], v[166:169], v[126:129]
	v_mfma_f32_16x16x32_bf16 v[114:117], v[134:137], v[174:177], v[114:117]
	v_mfma_f32_16x16x32_bf16 v[110:113], v[142:145], v[174:177], v[110:113]
	v_mfma_f32_16x16x32_bf16 v[98:101], v[134:137], v[182:185], v[98:101]
	v_mfma_f32_16x16x32_bf16 v[94:97], v[142:145], v[182:185], v[94:97]
	v_mfma_f32_16x16x32_bf16 v[82:85], v[134:137], v[190:193], v[82:85]
	v_mfma_f32_16x16x32_bf16 v[74:77], v[142:145], v[190:193], v[74:77]
	v_mfma_f32_16x16x32_bf16 v[130:133], v[138:141], v[170:173], v[130:133]
	v_mfma_f32_16x16x32_bf16 v[126:129], v[146:149], v[170:173], v[126:129]
	v_mfma_f32_16x16x32_bf16 v[114:117], v[138:141], v[178:181], v[114:117]
	v_mfma_f32_16x16x32_bf16 v[110:113], v[146:149], v[178:181], v[110:113]
	v_mfma_f32_16x16x32_bf16 v[98:101], v[138:141], v[186:189], v[98:101]
	v_mfma_f32_16x16x32_bf16 v[94:97], v[146:149], v[186:189], v[94:97]
	v_mfma_f32_16x16x32_bf16 v[82:85], v[138:141], v[194:197], v[82:85]
	v_mfma_f32_16x16x32_bf16 v[74:77], v[146:149], v[194:197], v[74:77]
	s_setprio 0
	s_setprio 1
	v_mfma_f32_16x16x32_bf16 v[122:125], v[150:153], v[166:169], v[122:125]
	v_mfma_f32_16x16x32_bf16 v[118:121], v[158:161], v[166:169], v[118:121]
	v_mfma_f32_16x16x32_bf16 v[106:109], v[150:153], v[174:177], v[106:109]
	v_mfma_f32_16x16x32_bf16 v[102:105], v[158:161], v[174:177], v[102:105]
	v_mfma_f32_16x16x32_bf16 v[90:93], v[150:153], v[182:185], v[90:93]
	v_mfma_f32_16x16x32_bf16 v[86:89], v[158:161], v[182:185], v[86:89]
	v_mfma_f32_16x16x32_bf16 v[66:69], v[150:153], v[190:193], v[66:69]
	v_mfma_f32_16x16x32_bf16 v[42:45], v[158:161], v[190:193], v[42:45]
	v_mfma_f32_16x16x32_bf16 v[122:125], v[154:157], v[170:173], v[122:125]
	v_mfma_f32_16x16x32_bf16 v[118:121], v[162:165], v[170:173], v[118:121]
	v_mfma_f32_16x16x32_bf16 v[106:109], v[154:157], v[178:181], v[106:109]
	v_mfma_f32_16x16x32_bf16 v[102:105], v[162:165], v[178:181], v[102:105]
	v_mfma_f32_16x16x32_bf16 v[90:93], v[154:157], v[186:189], v[90:93]
	v_mfma_f32_16x16x32_bf16 v[86:89], v[162:165], v[186:189], v[86:89]
	v_mfma_f32_16x16x32_bf16 v[66:69], v[154:157], v[194:197], v[66:69]
	v_mfma_f32_16x16x32_bf16 v[42:45], v[162:165], v[194:197], v[42:45]
.Lskiphalf_3:
	s_setprio 0
	s_barrier
	s_add_u32 s46, s46, 0x100
	s_addc_u32 s47, s47, 0
	s_cmp_ge_i32 s70, s3
	v_add_u32_e32 v237, s75, v237
	s_cbranch_scc1 .LBB0_387

; __device__ __forceinline__ unsigned cvt_pk_bf16(float lo, float hi) { unsigned r; asm volatile("v_cvt_pk_bf16_f32 %0, %1, %2" : "=v"(r) : "v"(lo), "v"(hi)); return r; }
;     __device__ __forceinline__ void operator()(const f32x4 (&acc)[2][2][4][2], const pg8::Unit& u, int wr, int wc, int fr, int fq) const {
;     ...
;             for (int m = 0; m < 4; ++m) { const int row = row0 + ai * 128 + m * 16;
;                 if (row < MV) {
;                     const float* rp = (row < MPR) ? res_p + (size_t)row * DM : res_s + (size_t)(row - MPR) * DM;
;                     float s = 0.f;
; #pragma unroll
;                     for (int bj = 0; bj < 2; ++bj)
; #pragma unroll
;                         for (int n = 0; n < 2; ++n) { const int col = col0 + bj * 128 + n * 16; f32x4 r;
;                             if (RESB) { const u32x2 rw = *(const u32x2*)(resb + (size_t)row * DM + col); r = (f32x4){bf2f(rw.x & 0xffff), bf2f(rw.x >> 16), bf2f(rw.y & 0xffff), bf2f(rw.y >> 16)}; }
;                             else r = *(const f32x4*)(rp + col);
;                             const f32x4 v = r + acc[ai][bj][m][n] * scale;
;                             if (OUTF) *(f32x4*)(out + (size_t)row * DM + col) = v;
;                             else { u32x2 w; w.x = cvt_pk_bf16(v[0], v[1]); w.y = cvt_pk_bf16(v[2], v[3]); *(u32x2*)(outb + (size_t)row * DM + col) = w;
;                                 s += (v[0] * v[0] + v[1] * v[1]) + (v[2] * v[2] + v[3] * v[3]); } }
.LBB0_389:
	s_cmp_lt_i32 s95, 2
	s_cbranch_scc0 .LBB0_449
	v_lshl_add_u32 v182, s94, 8, v230
	v_lshl_or_b32 v184, s44, 8, v233
	v_lshlrev_b32_e32 v182, 11, v182
	v_lshl_add_u32 v182, v184, 1, v182
	v_lshlrev_b32_e32 v183, 1, v182
	global_load_dwordx4 v[134:137], v183, s[16:17]
	global_load_dwordx4 v[138:141], v183, s[16:17] offset:64
	global_load_dwordx4 v[142:145], v183, s[16:17] offset:512
	global_load_dwordx4 v[146:149], v183, s[16:17] offset:576
	v_add_u32_e32 v184, 0x10000, v183
	global_load_dwordx4 v[150:153], v184, s[16:17]
	global_load_dwordx4 v[154:157], v184, s[16:17] offset:64
	global_load_dwordx4 v[158:161], v184, s[16:17] offset:512
	global_load_dwordx4 v[162:165], v184, s[16:17] offset:576
	v_add_u32_e32 v184, 0x20000, v183
	global_load_dwordx4 v[166:169], v184, s[16:17]
	global_load_dwordx4 v[170:173], v184, s[16:17] offset:64
	global_load_dwordx4 v[174:177], v184, s[16:17] offset:512
	global_load_dwordx4 v[178:181], v184, s[16:17] offset:576
	s_waitcnt vmcnt(8)
	v_fma_f32 v78, v78, 0.5, v134
	v_fma_f32 v79, v79, 0.5, v135
	v_fma_f32 v80, v80, 0.5, v136
	v_fma_f32 v81, v81, 0.5, v137
	v_mul_f32_e32 v134, v79, v79
	v_mul_f32_e32 v135, v81, v81
	v_fmac_f32_e32 v134, v78, v78
	v_fmac_f32_e32 v135, v80, v80
	v_add_f32_e32 v134, v134, v135
	v_mov_b32_e32 v185, v134
	v_cvt_pk_bf16_f32 v78, v78, v79
	v_cvt_pk_bf16_f32 v79, v80, v81
	v_fma_f32 v70, v70, 0.5, v138
	v_fma_f32 v71, v71, 0.5, v139
	v_fma_f32 v72, v72, 0.5, v140
	v_fma_f32 v73, v73, 0.5, v141
	v_mul_f32_e32 v138, v71, v71
	v_mul_f32_e32 v139, v73, v73
	v_fmac_f32_e32 v138, v70, v70
	v_fmac_f32_e32 v139, v72, v72
	v_add_f32_e32 v138, v138, v139
	v_add_f32_e32 v185, v185, v138
	v_cvt_pk_bf16_f32 v70, v70, v71
	v_cvt_pk_bf16_f32 v71, v72, v73
	v_fma_f32 v62, v62, 0.5, v142
	v_fma_f32 v63, v63, 0.5, v143
	v_fma_f32 v64, v64, 0.5, v144
	v_fma_f32 v65, v65, 0.5, v145
	v_mul_f32_e32 v142, v63, v63
	v_mul_f32_e32 v143, v65, v65
	v_fmac_f32_e32 v142, v62, v62
	v_fmac_f32_e32 v143, v64, v64
	v_add_f32_e32 v142, v142, v143
	v_add_f32_e32 v185, v185, v142
	v_cvt_pk_bf16_f32 v62, v62, v63
	v_cvt_pk_bf16_f32 v63, v64, v65
	v_fma_f32 v54, v54, 0.5, v146
	v_fma_f32 v55, v55, 0.5, v147
	v_fma_f32 v56, v56, 0.5, v148
	v_fma_f32 v57, v57, 0.5, v149
	v_mul_f32_e32 v146, v55, v55
	v_mul_f32_e32 v147, v57, v57
	v_fmac_f32_e32 v146, v54, v54
	v_fmac_f32_e32 v147, v56, v56
	v_add_f32_e32 v146, v146, v147
	v_add_f32_e32 v185, v185, v146
	v_cvt_pk_bf16_f32 v54, v54, v55
	v_cvt_pk_bf16_f32 v55, v56, v57
	v_mov_b32_e32 v80, v185
	v_add_u32_e32 v184, 0x30000, v183
	global_load_dwordx4 v[134:137], v184, s[16:17]
	global_load_dwordx4 v[138:141], v184, s[16:17] offset:64
	global_load_dwordx4 v[142:145], v184, s[16:17] offset:512
	global_load_dwordx4 v[146:149], v184, s[16:17] offset:576
	global_store_dwordx2 v182, v[78:79], s[28:29]
	global_store_dwordx2 v182, v[70:71], s[28:29] offset:32
	global_store_dwordx2 v182, v[62:63], s[28:29] offset:256
	global_store_dwordx2 v182, v[54:55], s[28:29] offset:288
	s_waitcnt vmcnt(12)
	v_fma_f32 v58, v58, 0.5, v150
	v_fma_f32 v59, v59, 0.5, v151
	v_fma_f32 v60, v60, 0.5, v152
	v_fma_f32 v61, v61, 0.5, v153
	v_mul_f32_e32 v150, v59, v59
	v_mul_f32_e32 v151, v61, v61
	v_fmac_f32_e32 v150, v58, v58
	v_fmac_f32_e32 v151, v60, v60
	v_add_f32_e32 v150, v150, v151
	v_mov_b32_e32 v185, v150
	v_cvt_pk_bf16_f32 v58, v58, v59
	v_cvt_pk_bf16_f32 v59, v60, v61
	v_fma_f32 v50, v50, 0.5, v154
	v_fma_f32 v51, v51, 0.5, v155
	v_fma_f32 v52, v52, 0.5, v156
	v_fma_f32 v53, v53, 0.5, v157
	v_mul_f32_e32 v154, v51, v51
	v_mul_f32_e32 v155, v53, v53
	v_fmac_f32_e32 v154, v50, v50
	v_fmac_f32_e32 v155, v52, v52
	v_add_f32_e32 v154, v154, v155
	v_add_f32_e32 v185, v185, v154
	v_cvt_pk_bf16_f32 v50, v50, v51
	v_cvt_pk_bf16_f32 v51, v52, v53
	v_fma_f32 v46, v46, 0.5, v158
	v_fma_f32 v47, v47, 0.5, v159
	v_fma_f32 v48, v48, 0.5, v160
	v_fma_f32 v49, v49, 0.5, v161
	v_mul_f32_e32 v158, v47, v47
	v_mul_f32_e32 v159, v49, v49
	v_fmac_f32_e32 v158, v46, v46
	v_fmac_f32_e32 v159, v48, v48
	v_add_f32_e32 v158, v158, v159
	v_add_f32_e32 v185, v185, v158
	v_cvt_pk_bf16_f32 v46, v46, v47
	v_cvt_pk_bf16_f32 v47, v48, v49
	v_fma_f32 v34, v34, 0.5, v162
	v_fma_f32 v35, v35, 0.5, v163
	v_fma_f32 v36, v36, 0.5, v164
	v_fma_f32 v37, v37, 0.5, v165
	v_mul_f32_e32 v162, v35, v35
	v_mul_f32_e32 v163, v37, v37
	v_fmac_f32_e32 v162, v34, v34
	v_fmac_f32_e32 v163, v36, v36
	v_add_f32_e32 v162, v162, v163
	v_add_f32_e32 v185, v185, v162
	v_cvt_pk_bf16_f32 v34, v34, v35
	v_cvt_pk_bf16_f32 v35, v36, v37
	v_mov_b32_e32 v60, v185
	v_add_u32_e32 v184, 0x80000, v183
	global_load_dwordx4 v[150:153], v184, s[16:17]
	global_load_dwordx4 v[154:157], v184, s[16:17] offset:64
	global_load_dwordx4 v[158:161], v184, s[16:17] offset:512
	global_load_dwordx4 v[162:165], v184, s[16:17] offset:576
	v_add_u32_e32 v184, 0x8000, v182
	global_store_dwordx2 v184, v[58:59], s[28:29]
	global_store_dwordx2 v184, v[50:51], s[28:29] offset:32
	global_store_dwordx2 v184, v[46:47], s[28:29] offset:256
	global_store_dwordx2 v184, v[34:35], s[28:29] offset:288
	s_waitcnt vmcnt(16)
; __device__ __forceinline__ unsigned cvt_pk_bf16(float lo, float hi) { unsigned r; asm volatile("v_cvt_pk_bf16_f32 %0, %1, %2" : "=v"(r) : "v"(lo), "v"(hi)); return r; }
;     __device__ __forceinline__ void operator()(const f32x4 (&acc)[2][2][4][2], const pg8::Unit& u, int wr, int wc, int fr, int fq) const {
;     ...
;                     for (int bj = 0; bj < 2; ++bj)
; #pragma unroll
;                         for (int n = 0; n < 2; ++n) { const int col = col0 + bj * 128 + n * 16; f32x4 r;
;                             if (RESB) { const u32x2 rw = *(const u32x2*)(resb + (size_t)row * DM + col); r = (f32x4){bf2f(rw.x & 0xffff), bf2f(rw.x >> 16), bf2f(rw.y & 0xffff), bf2f(rw.y >> 16)}; }
;                             else r = *(const f32x4*)(rp + col);
;                             const f32x4 v = r + acc[ai][bj][m][n] * scale;
;                             if (OUTF) *(f32x4*)(out + (size_t)row * DM + col) = v;
;                             else { u32x2 w; w.x = cvt_pk_bf16(v[0], v[1]); w.y = cvt_pk_bf16(v[2], v[3]); *(u32x2*)(outb + (size_t)row * DM + col) = w;
;                                 s += (v[0] * v[0] + v[1] * v[1]) + (v[2] * v[2] + v[3] * v[3]); } }
	v_fma_f32 v38, v38, 0.5, v166
	v_fma_f32 v39, v39, 0.5, v167
	v_fma_f32 v40, v40, 0.5, v168
	v_fma_f32 v41, v41, 0.5, v169
	v_mul_f32_e32 v166, v39, v39
	v_mul_f32_e32 v167, v41, v41
	v_fmac_f32_e32 v166, v38, v38
	v_fmac_f32_e32 v167, v40, v40
	v_add_f32_e32 v166, v166, v167
	v_mov_b32_e32 v185, v166
	v_cvt_pk_bf16_f32 v38, v38, v39
	v_cvt_pk_bf16_f32 v39, v40, v41
	v_fma_f32 v30, v30, 0.5, v170
	v_fma_f32 v31, v31, 0.5, v171
	v_fma_f32 v32, v32, 0.5, v172
	v_fma_f32 v33, v33, 0.5, v173
	v_mul_f32_e32 v170, v31, v31
	v_mul_f32_e32 v171, v33, v33
	v_fmac_f32_e32 v170, v30, v30
	v_fmac_f32_e32 v171, v32, v32
	v_add_f32_e32 v170, v170, v171
	v_add_f32_e32 v185, v185, v170
	v_cvt_pk_bf16_f32 v30, v30, v31
	v_cvt_pk_bf16_f32 v31, v32, v33
	v_fma_f32 v26, v26, 0.5, v174
	v_fma_f32 v27, v27, 0.5, v175
	v_fma_f32 v28, v28, 0.5, v176
	v_fma_f32 v29, v29, 0.5, v177
	v_mul_f32_e32 v174, v27, v27
	v_mul_f32_e32 v175, v29, v29
	v_fmac_f32_e32 v174, v26, v26
	v_fmac_f32_e32 v175, v28, v28
	v_add_f32_e32 v174, v174, v175
	v_add_f32_e32 v185, v185, v174
	v_cvt_pk_bf16_f32 v26, v26, v27
	v_cvt_pk_bf16_f32 v27, v28, v29
	v_fma_f32 v18, v18, 0.5, v178
	v_fma_f32 v19, v19, 0.5, v179
	v_fma_f32 v20, v20, 0.5, v180
	v_fma_f32 v21, v21, 0.5, v181
	v_mul_f32_e32 v178, v19, v19
	v_mul_f32_e32 v179, v21, v21
	v_fmac_f32_e32 v178, v18, v18
	v_fmac_f32_e32 v179, v20, v20
	v_add_f32_e32 v178, v178, v179
	v_add_f32_e32 v185, v185, v178
	v_cvt_pk_bf16_f32 v18, v18, v19
	v_cvt_pk_bf16_f32 v19, v20, v21
	v_mov_b32_e32 v40, v185
	v_add_u32_e32 v184, 0x90000, v183
	global_load_dwordx4 v[166:169], v184, s[16:17]
	global_load_dwordx4 v[170:173], v184, s[16:17] offset:64
	global_load_dwordx4 v[174:177], v184, s[16:17] offset:512
	global_load_dwordx4 v[178:181], v184, s[16:17] offset:576
	v_add_u32_e32 v184, 0x10000, v182
	global_store_dwordx2 v184, v[38:39], s[28:29]
	global_store_dwordx2 v184, v[30:31], s[28:29] offset:32
	global_store_dwordx2 v184, v[26:27], s[28:29] offset:256
	global_store_dwordx2 v184, v[18:19], s[28:29] offset:288
	s_waitcnt vmcnt(20)
	v_fma_f32 v22, v22, 0.5, v134
	v_fma_f32 v23, v23, 0.5, v135
	v_fma_f32 v24, v24, 0.5, v136
	v_fma_f32 v25, v25, 0.5, v137
	v_mul_f32_e32 v134, v23, v23
	v_mul_f32_e32 v135, v25, v25
	v_fmac_f32_e32 v134, v22, v22
	v_fmac_f32_e32 v135, v24, v24
	v_add_f32_e32 v134, v134, v135
	v_mov_b32_e32 v185, v134
	v_cvt_pk_bf16_f32 v22, v22, v23
	v_cvt_pk_bf16_f32 v23, v24, v25
	v_fma_f32 v14, v14, 0.5, v138
	v_fma_f32 v15, v15, 0.5, v139
	v_fma_f32 v16, v16, 0.5, v140
	v_fma_f32 v17, v17, 0.5, v141
	v_mul_f32_e32 v138, v15, v15
	v_mul_f32_e32 v139, v17, v17
	v_fmac_f32_e32 v138, v14, v14
	v_fmac_f32_e32 v139, v16, v16
	v_add_f32_e32 v138, v138, v139
	v_add_f32_e32 v185, v185, v138
	v_cvt_pk_bf16_f32 v14, v14, v15
	v_cvt_pk_bf16_f32 v15, v16, v17
	v_fma_f32 v10, v10, 0.5, v142
	v_fma_f32 v11, v11, 0.5, v143
	v_fma_f32 v12, v12, 0.5, v144
	v_fma_f32 v13, v13, 0.5, v145
	v_mul_f32_e32 v142, v11, v11
	v_mul_f32_e32 v143, v13, v13
	v_fmac_f32_e32 v142, v10, v10
	v_fmac_f32_e32 v143, v12, v12
	v_add_f32_e32 v142, v142, v143
	v_add_f32_e32 v185, v185, v142
	v_cvt_pk_bf16_f32 v10, v10, v11
	v_cvt_pk_bf16_f32 v11, v12, v13
	v_fma_f32 v6, v6, 0.5, v146
	v_fma_f32 v7, v7, 0.5, v147
	v_fma_f32 v8, v8, 0.5, v148
	v_fma_f32 v9, v9, 0.5, v149
	v_mul_f32_e32 v146, v7, v7
	v_mul_f32_e32 v147, v9, v9
	v_fmac_f32_e32 v146, v6, v6
	v_fmac_f32_e32 v147, v8, v8
	v_add_f32_e32 v146, v146, v147
	v_add_f32_e32 v185, v185, v146
	v_cvt_pk_bf16_f32 v6, v6, v7
	v_cvt_pk_bf16_f32 v7, v8, v9
	v_mov_b32_e32 v24, v185
	v_add_u32_e32 v184, 0xa0000, v183
	global_load_dwordx4 v[134:137], v184, s[16:17]
	global_load_dwordx4 v[138:141], v184, s[16:17] offset:64
	global_load_dwordx4 v[142:145], v184, s[16:17] offset:512
	global_load_dwordx4 v[146:149], v184, s[16:17] offset:576
	v_add_u32_e32 v184, 0x18000, v182
	global_store_dwordx2 v184, v[22:23], s[28:29]
	global_store_dwordx2 v184, v[14:15], s[28:29] offset:32
	global_store_dwordx2 v184, v[10:11], s[28:29] offset:256
	global_store_dwordx2 v184, v[6:7], s[28:29] offset:288
	s_waitcnt vmcnt(20)
	v_fma_f32 v130, v130, 0.5, v150
	v_fma_f32 v131, v131, 0.5, v151
	v_fma_f32 v132, v132, 0.5, v152
	v_fma_f32 v133, v133, 0.5, v153
	v_mul_f32_e32 v150, v131, v131
	v_mul_f32_e32 v151, v133, v133
	v_fmac_f32_e32 v150, v130, v130
	v_fmac_f32_e32 v151, v132, v132
	v_add_f32_e32 v150, v150, v151
	v_mov_b32_e32 v185, v150
	v_cvt_pk_bf16_f32 v130, v130, v131
	v_cvt_pk_bf16_f32 v131, v132, v133
	v_fma_f32 v126, v126, 0.5, v154
	v_fma_f32 v127, v127, 0.5, v155
	v_fma_f32 v128, v128, 0.5, v156
	v_fma_f32 v129, v129, 0.5, v157
	v_mul_f32_e32 v154, v127, v127
	v_mul_f32_e32 v155, v129, v129
	v_fmac_f32_e32 v154, v126, v126
	v_fmac_f32_e32 v155, v128, v128
	v_add_f32_e32 v154, v154, v155
	v_add_f32_e32 v185, v185, v154
	v_cvt_pk_bf16_f32 v126, v126, v127
	v_cvt_pk_bf16_f32 v127, v128, v129
	v_fma_f32 v122, v122, 0.5, v158
	v_fma_f32 v123, v123, 0.5, v159
	v_fma_f32 v124, v124, 0.5, v160
	v_fma_f32 v125, v125, 0.5, v161
	v_mul_f32_e32 v158, v123, v123
	v_mul_f32_e32 v159, v125, v125
	v_fmac_f32_e32 v158, v122, v122
	v_fmac_f32_e32 v159, v124, v124
	v_add_f32_e32 v158, v158, v159
	v_add_f32_e32 v185, v185, v158
	v_cvt_pk_bf16_f32 v122, v122, v123
	v_cvt_pk_bf16_f32 v123, v124, v125
	v_fma_f32 v118, v118, 0.5, v162
	v_fma_f32 v119, v119, 0.5, v163
	v_fma_f32 v120, v120, 0.5, v164
	v_fma_f32 v121, v121, 0.5, v165
	v_mul_f32_e32 v162, v119, v119
	v_mul_f32_e32 v163, v121, v121
	v_fmac_f32_e32 v162, v118, v118
	v_fmac_f32_e32 v163, v120, v120
	v_add_f32_e32 v162, v162, v163
	v_add_f32_e32 v185, v185, v162
	v_cvt_pk_bf16_f32 v118, v118, v119
	v_cvt_pk_bf16_f32 v119, v120, v121
	v_mov_b32_e32 v132, v185
	v_add_u32_e32 v184, 0xb0000, v183
	global_load_dwordx4 v[150:153], v184, s[16:17]
	global_load_dwordx4 v[154:157], v184, s[16:17] offset:64
	global_load_dwordx4 v[158:161], v184, s[16:17] offset:512
	global_load_dwordx4 v[162:165], v184, s[16:17] offset:576
	v_add_u32_e32 v184, 0x40000, v182
	global_store_dwordx2 v184, v[130:131], s[28:29]
	global_store_dwordx2 v184, v[126:127], s[28:29] offset:32
	global_store_dwordx2 v184, v[122:123], s[28:29] offset:256
	global_store_dwordx2 v184, v[118:119], s[28:29] offset:288
	s_waitcnt vmcnt(20)
; __device__ __forceinline__ unsigned cvt_pk_bf16(float lo, float hi) { unsigned r; asm volatile("v_cvt_pk_bf16_f32 %0, %1, %2" : "=v"(r) : "v"(lo), "v"(hi)); return r; }
;     __device__ __forceinline__ void operator()(const f32x4 (&acc)[2][2][4][2], const pg8::Unit& u, int wr, int wc, int fr, int fq) const {
;     ...
;                     for (int bj = 0; bj < 2; ++bj)
; #pragma unroll
;                         for (int n = 0; n < 2; ++n) { const int col = col0 + bj * 128 + n * 16; f32x4 r;
;                             if (RESB) { const u32x2 rw = *(const u32x2*)(resb + (size_t)row * DM + col); r = (f32x4){bf2f(rw.x & 0xffff), bf2f(rw.x >> 16), bf2f(rw.y & 0xffff), bf2f(rw.y >> 16)}; }
;                             else r = *(const f32x4*)(rp + col);
;                             const f32x4 v = r + acc[ai][bj][m][n] * scale;
;                             if (OUTF) *(f32x4*)(out + (size_t)row * DM + col) = v;
;                             else { u32x2 w; w.x = cvt_pk_bf16(v[0], v[1]); w.y = cvt_pk_bf16(v[2], v[3]); *(u32x2*)(outb + (size_t)row * DM + col) = w;
;                                 s += (v[0] * v[0] + v[1] * v[1]) + (v[2] * v[2] + v[3] * v[3]); } }
	v_fma_f32 v114, v114, 0.5, v166
	v_fma_f32 v115, v115, 0.5, v167
	v_fma_f32 v116, v116, 0.5, v168
	v_fma_f32 v117, v117, 0.5, v169
	v_mul_f32_e32 v166, v115, v115
	v_mul_f32_e32 v167, v117, v117
	v_fmac_f32_e32 v166, v114, v114
	v_fmac_f32_e32 v167, v116, v116
	v_add_f32_e32 v166, v166, v167
	v_mov_b32_e32 v185, v166
	v_cvt_pk_bf16_f32 v114, v114, v115
	v_cvt_pk_bf16_f32 v115, v116, v117
	v_fma_f32 v110, v110, 0.5, v170
	v_fma_f32 v111, v111, 0.5, v171
	v_fma_f32 v112, v112, 0.5, v172
	v_fma_f32 v113, v113, 0.5, v173
	v_mul_f32_e32 v170, v111, v111
	v_mul_f32_e32 v171, v113, v113
	v_fmac_f32_e32 v170, v110, v110
	v_fmac_f32_e32 v171, v112, v112
	v_add_f32_e32 v170, v170, v171
	v_add_f32_e32 v185, v185, v170
	v_cvt_pk_bf16_f32 v110, v110, v111
	v_cvt_pk_bf16_f32 v111, v112, v113
	v_fma_f32 v106, v106, 0.5, v174
	v_fma_f32 v107, v107, 0.5, v175
	v_fma_f32 v108, v108, 0.5, v176
	v_fma_f32 v109, v109, 0.5, v177
	v_mul_f32_e32 v174, v107, v107
	v_mul_f32_e32 v175, v109, v109
	v_fmac_f32_e32 v174, v106, v106
	v_fmac_f32_e32 v175, v108, v108
	v_add_f32_e32 v174, v174, v175
	v_add_f32_e32 v185, v185, v174
	v_cvt_pk_bf16_f32 v106, v106, v107
	v_cvt_pk_bf16_f32 v107, v108, v109
	v_fma_f32 v102, v102, 0.5, v178
	v_fma_f32 v103, v103, 0.5, v179
	v_fma_f32 v104, v104, 0.5, v180
	v_fma_f32 v105, v105, 0.5, v181
	v_mul_f32_e32 v178, v103, v103
	v_mul_f32_e32 v179, v105, v105
	v_fmac_f32_e32 v178, v102, v102
	v_fmac_f32_e32 v179, v104, v104
	v_add_f32_e32 v178, v178, v179
	v_add_f32_e32 v185, v185, v178
	v_cvt_pk_bf16_f32 v102, v102, v103
	v_cvt_pk_bf16_f32 v103, v104, v105
	v_mov_b32_e32 v116, v185
	v_add_u32_e32 v184, 0x48000, v182
	global_store_dwordx2 v184, v[114:115], s[28:29]
	global_store_dwordx2 v184, v[110:111], s[28:29] offset:32
	global_store_dwordx2 v184, v[106:107], s[28:29] offset:256
	global_store_dwordx2 v184, v[102:103], s[28:29] offset:288
	s_waitcnt vmcnt(16)
	v_fma_f32 v98, v98, 0.5, v134
	v_fma_f32 v99, v99, 0.5, v135
	v_fma_f32 v100, v100, 0.5, v136
	v_fma_f32 v101, v101, 0.5, v137
	v_mul_f32_e32 v134, v99, v99
	v_mul_f32_e32 v135, v101, v101
	v_fmac_f32_e32 v134, v98, v98
	v_fmac_f32_e32 v135, v100, v100
	v_add_f32_e32 v134, v134, v135
	v_mov_b32_e32 v185, v134
	v_cvt_pk_bf16_f32 v98, v98, v99
	v_cvt_pk_bf16_f32 v99, v100, v101
	v_fma_f32 v94, v94, 0.5, v138
	v_fma_f32 v95, v95, 0.5, v139
	v_fma_f32 v96, v96, 0.5, v140
	v_fma_f32 v97, v97, 0.5, v141
	v_mul_f32_e32 v138, v95, v95
	v_mul_f32_e32 v139, v97, v97
	v_fmac_f32_e32 v138, v94, v94
	v_fmac_f32_e32 v139, v96, v96
	v_add_f32_e32 v138, v138, v139
	v_add_f32_e32 v185, v185, v138
	v_cvt_pk_bf16_f32 v94, v94, v95
	v_cvt_pk_bf16_f32 v95, v96, v97
	v_fma_f32 v90, v90, 0.5, v142
	v_fma_f32 v91, v91, 0.5, v143
	v_fma_f32 v92, v92, 0.5, v144
	v_fma_f32 v93, v93, 0.5, v145
	v_mul_f32_e32 v142, v91, v91
	v_mul_f32_e32 v143, v93, v93
	v_fmac_f32_e32 v142, v90, v90
	v_fmac_f32_e32 v143, v92, v92
	v_add_f32_e32 v142, v142, v143
	v_add_f32_e32 v185, v185, v142
	v_cvt_pk_bf16_f32 v90, v90, v91
	v_cvt_pk_bf16_f32 v91, v92, v93
	v_fma_f32 v86, v86, 0.5, v146
	v_fma_f32 v87, v87, 0.5, v147
	v_fma_f32 v88, v88, 0.5, v148
	v_fma_f32 v89, v89, 0.5, v149
	v_mul_f32_e32 v146, v87, v87
	v_mul_f32_e32 v147, v89, v89
	v_fmac_f32_e32 v146, v86, v86
	v_fmac_f32_e32 v147, v88, v88
	v_add_f32_e32 v146, v146, v147
	v_add_f32_e32 v185, v185, v146
	v_cvt_pk_bf16_f32 v86, v86, v87
	v_cvt_pk_bf16_f32 v87, v88, v89
	v_mov_b32_e32 v100, v185
	v_add_u32_e32 v184, 0x50000, v182
	global_store_dwordx2 v184, v[98:99], s[28:29]
	global_store_dwordx2 v184, v[94:95], s[28:29] offset:32
	global_store_dwordx2 v184, v[90:91], s[28:29] offset:256
	global_store_dwordx2 v184, v[86:87], s[28:29] offset:288
	s_waitcnt vmcnt(12)
; __device__ __forceinline__ unsigned cvt_pk_bf16(float lo, float hi) { unsigned r; asm volatile("v_cvt_pk_bf16_f32 %0, %1, %2" : "=v"(r) : "v"(lo), "v"(hi)); return r; }
;     __device__ __forceinline__ void operator()(const f32x4 (&acc)[2][2][4][2], const pg8::Unit& u, int wr, int wc, int fr, int fq) const {
;     ...
;                     for (int bj = 0; bj < 2; ++bj)
; #pragma unroll
;                         for (int n = 0; n < 2; ++n) { const int col = col0 + bj * 128 + n * 16; f32x4 r;
;                             if (RESB) { const u32x2 rw = *(const u32x2*)(resb + (size_t)row * DM + col); r = (f32x4){bf2f(rw.x & 0xffff), bf2f(rw.x >> 16), bf2f(rw.y & 0xffff), bf2f(rw.y >> 16)}; }
;                             else r = *(const f32x4*)(rp + col);
;                             const f32x4 v = r + acc[ai][bj][m][n] * scale;
;                             if (OUTF) *(f32x4*)(out + (size_t)row * DM + col) = v;
;                             else { u32x2 w; w.x = cvt_pk_bf16(v[0], v[1]); w.y = cvt_pk_bf16(v[2], v[3]); *(u32x2*)(outb + (size_t)row * DM + col) = w;
;                                 s += (v[0] * v[0] + v[1] * v[1]) + (v[2] * v[2] + v[3] * v[3]); } }
;                     if (!OUTF) { s += __shfl_xor(s, 16); s += __shfl_xor(s, 32); if (fq == 0) atomicAdd(ss + row, s); }
	v_fma_f32 v82, v82, 0.5, v150
	v_fma_f32 v83, v83, 0.5, v151
	v_fma_f32 v84, v84, 0.5, v152
	v_fma_f32 v85, v85, 0.5, v153
	v_mul_f32_e32 v150, v83, v83
	v_mul_f32_e32 v151, v85, v85
	v_fmac_f32_e32 v150, v82, v82
	v_fmac_f32_e32 v151, v84, v84
	v_add_f32_e32 v150, v150, v151
	v_mov_b32_e32 v185, v150
	v_cvt_pk_bf16_f32 v82, v82, v83
	v_cvt_pk_bf16_f32 v83, v84, v85
	v_fma_f32 v74, v74, 0.5, v154
	v_fma_f32 v75, v75, 0.5, v155
	v_fma_f32 v76, v76, 0.5, v156
	v_fma_f32 v77, v77, 0.5, v157
	v_mul_f32_e32 v154, v75, v75
	v_mul_f32_e32 v155, v77, v77
	v_fmac_f32_e32 v154, v74, v74
	v_fmac_f32_e32 v155, v76, v76
	v_add_f32_e32 v154, v154, v155
	v_add_f32_e32 v185, v185, v154
	v_cvt_pk_bf16_f32 v74, v74, v75
	v_cvt_pk_bf16_f32 v75, v76, v77
	v_fma_f32 v66, v66, 0.5, v158
	v_fma_f32 v67, v67, 0.5, v159
	v_fma_f32 v68, v68, 0.5, v160
	v_fma_f32 v69, v69, 0.5, v161
	v_mul_f32_e32 v158, v67, v67
	v_mul_f32_e32 v159, v69, v69
	v_fmac_f32_e32 v158, v66, v66
	v_fmac_f32_e32 v159, v68, v68
	v_add_f32_e32 v158, v158, v159
	v_add_f32_e32 v185, v185, v158
	v_cvt_pk_bf16_f32 v66, v66, v67
	v_cvt_pk_bf16_f32 v67, v68, v69
	v_fma_f32 v42, v42, 0.5, v162
	v_fma_f32 v43, v43, 0.5, v163
	v_fma_f32 v44, v44, 0.5, v164
	v_fma_f32 v45, v45, 0.5, v165
	v_mul_f32_e32 v162, v43, v43
	v_mul_f32_e32 v163, v45, v45
	v_fmac_f32_e32 v162, v42, v42
	v_fmac_f32_e32 v163, v44, v44
	v_add_f32_e32 v162, v162, v163
	v_add_f32_e32 v185, v185, v162
	v_cvt_pk_bf16_f32 v42, v42, v43
	v_cvt_pk_bf16_f32 v43, v44, v45
	v_mov_b32_e32 v84, v185
	v_add_u32_e32 v184, 0x58000, v182
	global_store_dwordx2 v184, v[82:83], s[28:29]
	global_store_dwordx2 v184, v[74:75], s[28:29] offset:32
	global_store_dwordx2 v184, v[66:67], s[28:29] offset:256
	global_store_dwordx2 v184, v[42:43], s[28:29] offset:288
	v_xor_b32_e32 v186, 16, v236
	v_lshlrev_b32_e32 v186, 2, v186
	ds_bpermute_b32 v81, v186, v80
	ds_bpermute_b32 v61, v186, v60
	ds_bpermute_b32 v41, v186, v40
	ds_bpermute_b32 v25, v186, v24
	ds_bpermute_b32 v133, v186, v132
	ds_bpermute_b32 v117, v186, v116
	ds_bpermute_b32 v101, v186, v100
	ds_bpermute_b32 v85, v186, v84
	s_waitcnt lgkmcnt(0)
	v_add_f32_e32 v80, v80, v81
	v_add_f32_e32 v60, v60, v61
	v_add_f32_e32 v40, v40, v41
	v_add_f32_e32 v24, v24, v25
	v_add_f32_e32 v132, v132, v133
	v_add_f32_e32 v116, v116, v117
	v_add_f32_e32 v100, v100, v101
	v_add_f32_e32 v84, v84, v85
	v_xor_b32_e32 v186, 32, v236
	v_lshlrev_b32_e32 v186, 2, v186
	ds_bpermute_b32 v81, v186, v80
	ds_bpermute_b32 v61, v186, v60
	ds_bpermute_b32 v41, v186, v40
	ds_bpermute_b32 v25, v186, v24
	ds_bpermute_b32 v133, v186, v132
	ds_bpermute_b32 v117, v186, v116
	ds_bpermute_b32 v101, v186, v100
	ds_bpermute_b32 v85, v186, v84
	s_waitcnt lgkmcnt(0)
	v_add_f32_e32 v80, v80, v81
	v_add_f32_e32 v60, v60, v61
	v_add_f32_e32 v40, v40, v41
	v_add_f32_e32 v24, v24, v25
	v_add_f32_e32 v132, v132, v133
	v_add_f32_e32 v116, v116, v117
	v_add_f32_e32 v100, v100, v101
	v_add_f32_e32 v84, v84, v85
	v_lshl_add_u32 v182, s94, 8, v230
	v_lshlrev_b32_e32 v182, 2, v182
	s_and_saveexec_b64 s[0:1], s[8:9]
	global_atomic_add_f32 v182, v80, s[30:31]
	global_atomic_add_f32 v182, v60, s[30:31] offset:64
	global_atomic_add_f32 v182, v40, s[30:31] offset:128
	global_atomic_add_f32 v182, v24, s[30:31] offset:192
	global_atomic_add_f32 v182, v132, s[30:31] offset:512
	global_atomic_add_f32 v182, v116, s[30:31] offset:576
	global_atomic_add_f32 v182, v100, s[30:31] offset:640
	global_atomic_add_f32 v182, v84, s[30:31] offset:704
	s_or_b64 exec, exec, s[0:1]
	s_branch .Lp2e_done

; template <class Epi, class Sched, bool ALIGN_EPI = false, bool SP2 = false, class Bg = BgNone>
; __device__ __forceinline__ void gemm_phase(PG8_LAS unsigned char* lds, const Gemm g, const Sched& S, const Epi& E, const int wave_sg, const Bg& bg = Bg()) {
;     ...
;         } else
;         if constexpr (!Epi::AFTER_DRAIN) { E(acc, cur, wr, wc, fr, fq); S.done(cur); }
;         if (!has_next) break;
.Lp2e_done:
	s_and_b64 vcc, exec, s[12:13]
	s_mov_b64 s[0:1], -1
	s_cbranch_vccnz .LBB0_448

; #define PG8_STAGE(bufoff, gbase, voff) do { _Pragma("unroll") for (int _i = 0; _i < 2; ++_i) \
;         __builtin_amdgcn_global_load_lds((const unsigned*)((const char*)(gbase) + (voff)[_i]), (PG8_LAS unsigned*)(lds + (bufoff) + ldsw + _i * 8192), 16, 0, 0); } while (0)
; #define PG8_LDA(dst, b, h) do { _Pragma("unroll") for (int m = 0; m < 4; ++m) _Pragma("unroll") for (int k = 0; k < 2; ++k) dst[m][k] = *(const PG8_LAS bf16x8*)(lds + PG8_SA(b, h) + aoff + m * 2048 + k * 1024); } while (0)
; #define PG8_LDB(dst, b, h) do { _Pragma("unroll") for (int n = 0; n < 2; ++n) _Pragma("unroll") for (int k = 0; k < 2; ++k) dst[n][k] = *(const PG8_LAS bf16x8*)(lds + PG8_SB(b, h) + boff + n * 2048 + k * 1024); } while (0)
; #define PG8_MMA(ai, bj, At, Bt) do { __builtin_amdgcn_s_setprio(1); _Pragma("unroll") for (int m = 0; m < 4; ++m) _Pragma("unroll") for (int n = 0; n < 2; ++n) _Pragma("unroll") for (int k = 0; k < 2; ++k) \
;         acc[ai][bj][m][n] = __builtin_amdgcn_mfma_f32_16x16x32_bf16(Bt[n][k], At[m][k], acc[ai][bj][m][n], 0, 0, 0); __builtin_amdgcn_s_setprio(0); } while (0)
; #define PG8_WAIT_V(n) asm volatile("s_waitcnt vmcnt(" #n ")" ::: "memory")
; #define PG8_WAIT_L(n) asm volatile("s_waitcnt lgkmcnt(" #n ")" ::: "memory")
; #define PG8_BAR __builtin_amdgcn_s_barrier()
; #define PG8_SCHED __builtin_amdgcn_sched_barrier(0)
; template <class Epi, class Sched, bool ALIGN_EPI = false, bool SP2 = false, class Bg = BgNone>
; __device__ __forceinline__ void gemm_phase(PG8_LAS unsigned char* lds, const Gemm g, const Sched& S, const Epi& E, const int wave_sg, const Bg& bg = Bg()) {
;     ...
;             if (bg_on) { PG8_WAIT_V(10); } else { PG8_WAIT_V(8); } PG8_WAIT_L(0); PG8_BAR; PG8_MMA(1, 0, At, B0); PG8_MMA(1, 1, At, B1); PG8_BAR; PG8_SCHED;
;             PG8_LDB(B0, 1, 0); PG8_LDB(B1, 1, 1); PG8_SCHED; PG8_LDA(At, 1, 0); PG8_STAGE(PG8_SA(0, 1), a2 + hstep, voffA);
;             PG8_WAIT_V(8); PG8_WAIT_L(0); PG8_BAR; PG8_MMA(0, 0, At, B0); PG8_MMA(0, 1, At, B1); PG8_BAR; PG8_SCHED;
.LBB0_587:
	s_waitcnt lgkmcnt(0)
	s_barrier
	s_setprio 1
	s_waitcnt lgkmcnt(0)
	s_cmpk_eq_u32 s4, 0x80
	s_cbranch_scc1 .Lskiphalf_4
	v_mfma_f32_16x16x32_bf16 v[66:69], v[150:153], v[190:193], v[66:69]
	v_mfma_f32_16x16x32_bf16 v[62:65], v[158:161], v[190:193], v[62:65]
	v_mfma_f32_16x16x32_bf16 v[50:53], v[150:153], v[182:185], v[50:53]
	v_mfma_f32_16x16x32_bf16 v[46:49], v[158:161], v[182:185], v[46:49]
	v_mfma_f32_16x16x32_bf16 v[34:37], v[150:153], v[174:177], v[34:37]
	v_mfma_f32_16x16x32_bf16 v[30:33], v[158:161], v[174:177], v[30:33]
	v_mfma_f32_16x16x32_bf16 v[18:21], v[150:153], v[166:169], v[18:21]
	v_mfma_f32_16x16x32_bf16 v[14:17], v[158:161], v[166:169], v[14:17]
	v_mfma_f32_16x16x32_bf16 v[66:69], v[154:157], v[194:197], v[66:69]
	v_mfma_f32_16x16x32_bf16 v[62:65], v[162:165], v[194:197], v[62:65]
	v_mfma_f32_16x16x32_bf16 v[50:53], v[154:157], v[186:189], v[50:53]
	v_mfma_f32_16x16x32_bf16 v[46:49], v[162:165], v[186:189], v[46:49]
	v_mfma_f32_16x16x32_bf16 v[34:37], v[154:157], v[178:181], v[34:37]
	v_mfma_f32_16x16x32_bf16 v[30:33], v[162:165], v[178:181], v[30:33]
	v_mfma_f32_16x16x32_bf16 v[18:21], v[154:157], v[170:173], v[18:21]
	v_mfma_f32_16x16x32_bf16 v[14:17], v[162:165], v[170:173], v[14:17]
	s_setprio 0
	s_setprio 1
	v_mfma_f32_16x16x32_bf16 v[58:61], v[134:137], v[190:193], v[58:61]
	v_mfma_f32_16x16x32_bf16 v[54:57], v[142:145], v[190:193], v[54:57]
	v_mfma_f32_16x16x32_bf16 v[42:45], v[134:137], v[182:185], v[42:45]
	v_mfma_f32_16x16x32_bf16 v[38:41], v[142:145], v[182:185], v[38:41]
	v_mfma_f32_16x16x32_bf16 v[26:29], v[134:137], v[174:177], v[26:29]
	v_mfma_f32_16x16x32_bf16 v[22:25], v[142:145], v[174:177], v[22:25]
	v_mfma_f32_16x16x32_bf16 v[10:13], v[134:137], v[166:169], v[10:13]
	v_mfma_f32_16x16x32_bf16 v[6:9], v[142:145], v[166:169], v[6:9]
	v_mfma_f32_16x16x32_bf16 v[58:61], v[138:141], v[194:197], v[58:61]
	v_mfma_f32_16x16x32_bf16 v[54:57], v[146:149], v[194:197], v[54:57]
	v_mfma_f32_16x16x32_bf16 v[42:45], v[138:141], v[186:189], v[42:45]
	v_mfma_f32_16x16x32_bf16 v[38:41], v[146:149], v[186:189], v[38:41]
	v_mfma_f32_16x16x32_bf16 v[26:29], v[138:141], v[178:181], v[26:29]
	v_mfma_f32_16x16x32_bf16 v[22:25], v[146:149], v[178:181], v[22:25]
	v_mfma_f32_16x16x32_bf16 v[10:13], v[138:141], v[170:173], v[10:13]
	v_mfma_f32_16x16x32_bf16 v[6:9], v[146:149], v[170:173], v[6:9]
.Lskiphalf_4:
	s_setprio 0
	s_barrier
	s_add_i32 s43, 0, 0x18000
	v_add_u32_e32 v0, s43, v233
	s_add_i32 s56, 0, 0x1c000
	ds_read_b128 v[134:137], v0
	ds_read_b128 v[138:141], v0 offset:1024
	ds_read_b128 v[142:145], v0 offset:2048
	ds_read_b128 v[146:149], v0 offset:3072
	v_add_u32_e32 v0, s56, v233
	ds_read_b128 v[150:153], v0
	ds_read_b128 v[154:157], v0 offset:1024
	ds_read_b128 v[158:161], v0 offset:2048
	ds_read_b128 v[162:165], v0 offset:3072
	s_add_u32 s54, s54, 0x40000
	s_addc_u32 s55, s55, 0
	s_mov_b32 m0, s81
	v_lshl_add_u64 v[240:241], s[54:55], 0, v[198:199]
	ds_read_b128 v[166:169], v237 offset:32768
	ds_read_b128 v[170:173], v237 offset:33792
	ds_read_b128 v[174:177], v237 offset:34816
	ds_read_b128 v[178:181], v237 offset:35840
	ds_read_b128 v[182:185], v237 offset:36864
	ds_read_b128 v[186:189], v237 offset:37888
	ds_read_b128 v[190:193], v237 offset:38912
	ds_read_b128 v[194:197], v237 offset:39936
	global_load_lds_dwordx4 v[240:241], off
	v_lshl_add_u64 v[240:241], s[54:55], 0, v[200:201]
	s_mov_b32 m0, s82
	s_nop 0
	global_load_lds_dwordx4 v[240:241], off
	s_waitcnt vmcnt(8)
	s_waitcnt lgkmcnt(0)
	s_barrier
	s_setprio 1
	s_waitcnt lgkmcnt(0)
	v_mfma_f32_16x16x32_bf16 v[130:133], v[134:137], v[166:169], v[130:133]
	v_mfma_f32_16x16x32_bf16 v[126:129], v[142:145], v[166:169], v[126:129]
	v_mfma_f32_16x16x32_bf16 v[114:117], v[134:137], v[174:177], v[114:117]
	v_mfma_f32_16x16x32_bf16 v[110:113], v[142:145], v[174:177], v[110:113]
	v_mfma_f32_16x16x32_bf16 v[98:101], v[134:137], v[182:185], v[98:101]
	v_mfma_f32_16x16x32_bf16 v[94:97], v[142:145], v[182:185], v[94:97]
	v_mfma_f32_16x16x32_bf16 v[82:85], v[134:137], v[190:193], v[82:85]
	v_mfma_f32_16x16x32_bf16 v[78:81], v[142:145], v[190:193], v[78:81]
	v_mfma_f32_16x16x32_bf16 v[130:133], v[138:141], v[170:173], v[130:133]
	v_mfma_f32_16x16x32_bf16 v[126:129], v[146:149], v[170:173], v[126:129]
	v_mfma_f32_16x16x32_bf16 v[114:117], v[138:141], v[178:181], v[114:117]
	v_mfma_f32_16x16x32_bf16 v[110:113], v[146:149], v[178:181], v[110:113]
	v_mfma_f32_16x16x32_bf16 v[98:101], v[138:141], v[186:189], v[98:101]
	v_mfma_f32_16x16x32_bf16 v[94:97], v[146:149], v[186:189], v[94:97]
	v_mfma_f32_16x16x32_bf16 v[82:85], v[138:141], v[194:197], v[82:85]
	v_mfma_f32_16x16x32_bf16 v[78:81], v[146:149], v[194:197], v[78:81]
	s_setprio 0
	s_setprio 1
	v_mfma_f32_16x16x32_bf16 v[122:125], v[150:153], v[166:169], v[122:125]
	v_mfma_f32_16x16x32_bf16 v[118:121], v[158:161], v[166:169], v[118:121]
	v_mfma_f32_16x16x32_bf16 v[106:109], v[150:153], v[174:177], v[106:109]
	v_mfma_f32_16x16x32_bf16 v[102:105], v[158:161], v[174:177], v[102:105]
	v_mfma_f32_16x16x32_bf16 v[90:93], v[150:153], v[182:185], v[90:93]
	v_mfma_f32_16x16x32_bf16 v[86:89], v[158:161], v[182:185], v[86:89]
	v_mfma_f32_16x16x32_bf16 v[74:77], v[150:153], v[190:193], v[74:77]
	v_mfma_f32_16x16x32_bf16 v[70:73], v[158:161], v[190:193], v[70:73]
	v_mfma_f32_16x16x32_bf16 v[122:125], v[154:157], v[170:173], v[122:125]
	v_mfma_f32_16x16x32_bf16 v[118:121], v[162:165], v[170:173], v[118:121]
	v_mfma_f32_16x16x32_bf16 v[106:109], v[154:157], v[178:181], v[106:109]
	v_mfma_f32_16x16x32_bf16 v[102:105], v[162:165], v[178:181], v[102:105]
	v_mfma_f32_16x16x32_bf16 v[90:93], v[154:157], v[186:189], v[90:93]
	v_mfma_f32_16x16x32_bf16 v[86:89], v[162:165], v[186:189], v[86:89]
	v_mfma_f32_16x16x32_bf16 v[74:77], v[154:157], v[194:197], v[74:77]
	v_mfma_f32_16x16x32_bf16 v[70:73], v[162:165], v[194:197], v[70:73]
	s_setprio 0
	s_barrier
; #define PG8_STAGE(bufoff, gbase, voff) do { _Pragma("unroll") for (int _i = 0; _i < 2; ++_i) \
;         __builtin_amdgcn_global_load_lds((const unsigned*)((const char*)(gbase) + (voff)[_i]), (PG8_LAS unsigned*)(lds + (bufoff) + ldsw + _i * 8192), 16, 0, 0); } while (0)
; #define PG8_LDA(dst, b, h) do { _Pragma("unroll") for (int m = 0; m < 4; ++m) _Pragma("unroll") for (int k = 0; k < 2; ++k) dst[m][k] = *(const PG8_LAS bf16x8*)(lds + PG8_SA(b, h) + aoff + m * 2048 + k * 1024); } while (0)
; #define PG8_MMA(ai, bj, At, Bt) do { __builtin_amdgcn_s_setprio(1); _Pragma("unroll") for (int m = 0; m < 4; ++m) _Pragma("unroll") for (int n = 0; n < 2; ++n) _Pragma("unroll") for (int k = 0; k < 2; ++k) \
;         acc[ai][bj][m][n] = __builtin_amdgcn_mfma_f32_16x16x32_bf16(Bt[n][k], At[m][k], acc[ai][bj][m][n], 0, 0, 0); __builtin_amdgcn_s_setprio(0); } while (0)
; #define PG8_WAIT_V(n) asm volatile("s_waitcnt vmcnt(" #n ")" ::: "memory")
; #define PG8_WAIT_L(n) asm volatile("s_waitcnt lgkmcnt(" #n ")" ::: "memory")
; #define PG8_BAR __builtin_amdgcn_s_barrier()
; #define PG8_SCHED __builtin_amdgcn_sched_barrier(0)
; template <class Epi, class Sched, bool ALIGN_EPI = false, bool SP2 = false, class Bg = BgNone>
; __device__ __forceinline__ void gemm_phase(PG8_LAS unsigned char* lds, const Gemm g, const Sched& S, const Epi& E, const int wave_sg, const Bg& bg = Bg()) {
;     ...
;             PG8_LDA(At, 1, 1); PG8_STAGE(PG8_SB(1, 0), b3, voffB); PG8_STAGE(PG8_SB(1, 1), b3 + hstep, voffB); PG8_STAGE(PG8_SA(1, 0), a3, voffA);
;             PG8_WAIT_V(8); PG8_WAIT_L(0); PG8_BAR; PG8_MMA(1, 0, At, B0); PG8_MMA(1, 1, At, B1); PG8_BAR; PG8_SCHED;
	s_add_i32 s43, s43, s74
	v_lshl_add_u64 v[230:231], v[230:231], 0, s[34:35]
	s_mov_b32 m0, s43
	ds_read_b128 v[166:169], v237 offset:49152
	ds_read_b128 v[170:173], v237 offset:50176
	ds_read_b128 v[174:177], v237 offset:51200
	ds_read_b128 v[178:181], v237 offset:52224
	ds_read_b128 v[182:185], v237 offset:53248
	ds_read_b128 v[186:189], v237 offset:54272
	ds_read_b128 v[190:193], v237 offset:55296
	ds_read_b128 v[194:197], v237 offset:56320
	global_load_lds_dwordx4 v[230:231], off
	s_add_i32 m0, s43, 0x2000
	s_add_u32 s52, s52, 0x40080
	v_lshl_add_u64 v[228:229], v[228:229], 0, s[34:35]
	s_addc_u32 s53, s53, 0
	s_add_i32 s43, s56, s74
	global_load_lds_dwordx4 v[228:229], off
	v_lshl_add_u64 v[228:229], s[52:53], 0, v[198:199]
	s_mov_b32 m0, s43
	v_lshl_add_u64 v[224:225], v[224:225], 0, s[34:35]
	global_load_lds_dwordx4 v[228:229], off
	v_lshl_add_u64 v[228:229], s[52:53], 0, v[200:201]
	s_add_i32 m0, s43, 0x2000
	s_nop 0
	global_load_lds_dwordx4 v[228:229], off
	s_mov_b32 m0, s85
	s_nop 0
	global_load_lds_dwordx4 v[224:225], off
	v_lshl_add_u64 v[224:225], v[226:227], 0, s[34:35]
	s_mov_b32 m0, s86
	s_nop 0
	global_load_lds_dwordx4 v[224:225], off
	s_waitcnt vmcnt(8)
	s_waitcnt lgkmcnt(0)
	s_barrier
	s_setprio 1
	s_waitcnt lgkmcnt(0)
	s_cmpk_eq_u32 s4, 0x80
	s_cbranch_scc1 .Lskiphalf_5
	v_mfma_f32_16x16x32_bf16 v[66:69], v[134:137], v[166:169], v[66:69]
	v_mfma_f32_16x16x32_bf16 v[62:65], v[142:145], v[166:169], v[62:65]
	v_mfma_f32_16x16x32_bf16 v[50:53], v[134:137], v[174:177], v[50:53]
	v_mfma_f32_16x16x32_bf16 v[46:49], v[142:145], v[174:177], v[46:49]
	v_mfma_f32_16x16x32_bf16 v[34:37], v[134:137], v[182:185], v[34:37]
	v_mfma_f32_16x16x32_bf16 v[30:33], v[142:145], v[182:185], v[30:33]
	v_mfma_f32_16x16x32_bf16 v[18:21], v[134:137], v[190:193], v[18:21]
	v_mfma_f32_16x16x32_bf16 v[14:17], v[142:145], v[190:193], v[14:17]
	v_mfma_f32_16x16x32_bf16 v[66:69], v[138:141], v[170:173], v[66:69]
	v_mfma_f32_16x16x32_bf16 v[62:65], v[146:149], v[170:173], v[62:65]
	v_mfma_f32_16x16x32_bf16 v[50:53], v[138:141], v[178:181], v[50:53]
	v_mfma_f32_16x16x32_bf16 v[46:49], v[146:149], v[178:181], v[46:49]
	v_mfma_f32_16x16x32_bf16 v[34:37], v[138:141], v[186:189], v[34:37]
	v_mfma_f32_16x16x32_bf16 v[30:33], v[146:149], v[186:189], v[30:33]
	v_mfma_f32_16x16x32_bf16 v[18:21], v[138:141], v[194:197], v[18:21]
	v_mfma_f32_16x16x32_bf16 v[14:17], v[146:149], v[194:197], v[14:17]
	s_setprio 0
	s_setprio 1
	v_mfma_f32_16x16x32_bf16 v[58:61], v[150:153], v[166:169], v[58:61]
	v_mfma_f32_16x16x32_bf16 v[54:57], v[158:161], v[166:169], v[54:57]
	v_mfma_f32_16x16x32_bf16 v[42:45], v[150:153], v[174:177], v[42:45]
	v_mfma_f32_16x16x32_bf16 v[38:41], v[158:161], v[174:177], v[38:41]
	v_mfma_f32_16x16x32_bf16 v[26:29], v[150:153], v[182:185], v[26:29]
	v_mfma_f32_16x16x32_bf16 v[22:25], v[158:161], v[182:185], v[22:25]
	v_mfma_f32_16x16x32_bf16 v[10:13], v[150:153], v[190:193], v[10:13]
	v_mfma_f32_16x16x32_bf16 v[6:9], v[158:161], v[190:193], v[6:9]
	v_mfma_f32_16x16x32_bf16 v[58:61], v[154:157], v[170:173], v[58:61]
	v_mfma_f32_16x16x32_bf16 v[54:57], v[162:165], v[170:173], v[54:57]
	v_mfma_f32_16x16x32_bf16 v[42:45], v[154:157], v[178:181], v[42:45]
	v_mfma_f32_16x16x32_bf16 v[38:41], v[162:165], v[178:181], v[38:41]
	v_mfma_f32_16x16x32_bf16 v[26:29], v[154:157], v[186:189], v[26:29]
	v_mfma_f32_16x16x32_bf16 v[22:25], v[162:165], v[186:189], v[22:25]
	v_mfma_f32_16x16x32_bf16 v[10:13], v[154:157], v[194:197], v[10:13]
	v_mfma_f32_16x16x32_bf16 v[6:9], v[162:165], v[194:197], v[6:9]
.Lskiphalf_5:
	s_setprio 0
	s_barrier
	s_add_i32 s41, s41, 2
	s_add_u32 s50, s50, 0x100
	s_addc_u32 s51, s51, 0
	s_cmp_gt_u32 s41, 13
	v_add_u32_e32 v239, s94, v239
	s_cbranch_scc1 .LBB0_598

; #define PG8_STAGE(bufoff, gbase, voff) do { _Pragma("unroll") for (int _i = 0; _i < 2; ++_i) \
;         __builtin_amdgcn_global_load_lds((const unsigned*)((const char*)(gbase) + (voff)[_i]), (PG8_LAS unsigned*)(lds + (bufoff) + ldsw + _i * 8192), 16, 0, 0); } while (0)
; #define PG8_LDA(dst, b, h) do { _Pragma("unroll") for (int m = 0; m < 4; ++m) _Pragma("unroll") for (int k = 0; k < 2; ++k) dst[m][k] = *(const PG8_LAS bf16x8*)(lds + PG8_SA(b, h) + aoff + m * 2048 + k * 1024); } while (0)
; #define PG8_LDB(dst, b, h) do { _Pragma("unroll") for (int n = 0; n < 2; ++n) _Pragma("unroll") for (int k = 0; k < 2; ++k) dst[n][k] = *(const PG8_LAS bf16x8*)(lds + PG8_SB(b, h) + boff + n * 2048 + k * 1024); } while (0)
; #define PG8_MMA(ai, bj, At, Bt) do { __builtin_amdgcn_s_setprio(1); _Pragma("unroll") for (int m = 0; m < 4; ++m) _Pragma("unroll") for (int n = 0; n < 2; ++n) _Pragma("unroll") for (int k = 0; k < 2; ++k) \
;         acc[ai][bj][m][n] = __builtin_amdgcn_mfma_f32_16x16x32_bf16(Bt[n][k], At[m][k], acc[ai][bj][m][n], 0, 0, 0); __builtin_amdgcn_s_setprio(0); } while (0)
; #define PG8_WAIT_V(n) asm volatile("s_waitcnt vmcnt(" #n ")" ::: "memory")
; #define PG8_WAIT_L(n) asm volatile("s_waitcnt lgkmcnt(" #n ")" ::: "memory")
; #define PG8_BAR __builtin_amdgcn_s_barrier()
; #define PG8_SCHED __builtin_amdgcn_sched_barrier(0)
; template <class Epi, class Sched, bool ALIGN_EPI = false, bool SP2 = false, class Bg = BgNone>
; __device__ __forceinline__ void gemm_phase(PG8_LAS unsigned char* lds, const Gemm g, const Sched& S, const Epi& E, const int wave_sg, const Bg& bg = Bg()) {
;     ...
;             PG8_LDB(B0, 0, 0); PG8_LDB(B1, 0, 1); PG8_SCHED; PG8_LDA(At, 0, 0); PG8_STAGE(PG8_SA(1, 1), a1 + hstep, voffA);
;             if (bg_on) { PG8_WAIT_V(10); } else { PG8_WAIT_V(8); } PG8_WAIT_L(0); PG8_BAR; PG8_MMA(0, 0, At, B0); PG8_MMA(0, 1, At, B1); PG8_BAR; PG8_SCHED;
;             PG8_LDA(At, 0, 1); PG8_STAGE(PG8_SB(0, 0), b2, voffB); PG8_STAGE(PG8_SB(0, 1), b2 + hstep, voffB); PG8_STAGE(PG8_SA(0, 0), a2, voffA);
;             if (bg_on) { PG8_WAIT_V(10); } else { PG8_WAIT_V(8); } PG8_WAIT_L(0); PG8_BAR; PG8_MMA(1, 0, At, B0); PG8_MMA(1, 1, At, B1); PG8_BAR; PG8_SCHED;
.LBB0_965:
	s_add_u32 s0, s4, s6
	s_addc_u32 s1, s5, s7
	s_add_u32 s0, s0, 0x100
	s_addc_u32 s1, s1, 0
	s_add_u32 s49, s46, s6
	s_addc_u32 s50, s47, s7
	s_add_i32 s51, 0, 0x10000
	v_add_u32_e32 v1, s51, v184
	ds_read_b128 v[132:135], v1
	ds_read_b128 v[136:139], v1 offset:1024
	ds_read_b128 v[140:143], v1 offset:2048
	ds_read_b128 v[144:147], v1 offset:3072
	v_add_u32_e32 v1, s43, v184
	ds_read_b128 v[148:151], v1
	ds_read_b128 v[152:155], v1 offset:1024
	ds_read_b128 v[156:159], v1 offset:2048
	ds_read_b128 v[190:193], v1 offset:3072
	s_cmpk_eq_i32 s6, 0x500
	s_cselect_b32 s25, s11, s1
	s_cselect_b32 s24, s10, s0
	s_cselect_b32 s1, s23, s50
	s_cselect_b32 s0, s22, s49
	v_lshl_add_u64 v[2:3], v[178:179], 0, s[6:7]
	s_add_i32 m0, s31, 0xc000
	ds_read_b128 v[194:197], v187
	ds_read_b128 v[198:201], v187 offset:1024
	ds_read_b128 v[202:205], v187 offset:2048
	ds_read_b128 v[206:209], v187 offset:3072
	ds_read_b128 v[210:213], v187 offset:4096
	ds_read_b128 v[214:217], v187 offset:5120
	ds_read_b128 v[218:221], v187 offset:6144
	ds_read_b128 v[222:225], v187 offset:7168
	global_load_lds_dwordx4 v[2:3], off
	v_lshl_add_u64 v[2:3], v[180:181], 0, s[6:7]
	s_add_i32 m0, s31, 0xe000
	s_nop 0
	global_load_lds_dwordx4 v[2:3], off
	s_waitcnt vmcnt(8)
	s_waitcnt lgkmcnt(0)
	s_barrier
	s_setprio 1
	s_waitcnt lgkmcnt(0)
	v_mfma_f32_16x16x32_bf16 v[128:131], v[132:135], v[194:197], v[128:131]
	v_mfma_f32_16x16x32_bf16 v[124:127], v[140:143], v[194:197], v[124:127]
	v_mfma_f32_16x16x32_bf16 v[112:115], v[132:135], v[202:205], v[112:115]
	v_mfma_f32_16x16x32_bf16 v[108:111], v[140:143], v[202:205], v[108:111]
	v_mfma_f32_16x16x32_bf16 v[96:99], v[132:135], v[210:213], v[96:99]
	v_mfma_f32_16x16x32_bf16 v[92:95], v[140:143], v[210:213], v[92:95]
	v_mfma_f32_16x16x32_bf16 v[80:83], v[132:135], v[218:221], v[80:83]
	v_mfma_f32_16x16x32_bf16 v[76:79], v[140:143], v[218:221], v[76:79]
	v_mfma_f32_16x16x32_bf16 v[128:131], v[136:139], v[198:201], v[128:131]
	v_mfma_f32_16x16x32_bf16 v[124:127], v[144:147], v[198:201], v[124:127]
	v_mfma_f32_16x16x32_bf16 v[112:115], v[136:139], v[206:209], v[112:115]
	v_mfma_f32_16x16x32_bf16 v[108:111], v[144:147], v[206:209], v[108:111]
	v_mfma_f32_16x16x32_bf16 v[96:99], v[136:139], v[214:217], v[96:99]
	v_mfma_f32_16x16x32_bf16 v[92:95], v[144:147], v[214:217], v[92:95]
	v_mfma_f32_16x16x32_bf16 v[80:83], v[136:139], v[222:225], v[80:83]
	v_mfma_f32_16x16x32_bf16 v[76:79], v[144:147], v[222:225], v[76:79]
	s_setprio 0
	s_setprio 1
	v_mfma_f32_16x16x32_bf16 v[120:123], v[148:151], v[194:197], v[120:123]
	v_mfma_f32_16x16x32_bf16 v[116:119], v[156:159], v[194:197], v[116:119]
	v_mfma_f32_16x16x32_bf16 v[104:107], v[148:151], v[202:205], v[104:107]
	v_mfma_f32_16x16x32_bf16 v[100:103], v[156:159], v[202:205], v[100:103]
	v_mfma_f32_16x16x32_bf16 v[88:91], v[148:151], v[210:213], v[88:91]
	v_mfma_f32_16x16x32_bf16 v[84:87], v[156:159], v[210:213], v[84:87]
	v_mfma_f32_16x16x32_bf16 v[72:75], v[148:151], v[218:221], v[72:75]
	v_mfma_f32_16x16x32_bf16 v[68:71], v[156:159], v[218:221], v[68:71]
	v_mfma_f32_16x16x32_bf16 v[120:123], v[152:155], v[198:201], v[120:123]
	v_mfma_f32_16x16x32_bf16 v[116:119], v[190:193], v[198:201], v[116:119]
	v_mfma_f32_16x16x32_bf16 v[104:107], v[152:155], v[206:209], v[104:107]
	v_mfma_f32_16x16x32_bf16 v[100:103], v[190:193], v[206:209], v[100:103]
	v_mfma_f32_16x16x32_bf16 v[88:91], v[152:155], v[214:217], v[88:91]
	v_mfma_f32_16x16x32_bf16 v[84:87], v[190:193], v[214:217], v[84:87]
	v_mfma_f32_16x16x32_bf16 v[72:75], v[152:155], v[222:225], v[72:75]
	v_mfma_f32_16x16x32_bf16 v[68:71], v[190:193], v[222:225], v[68:71]
	s_setprio 0
	s_barrier
	s_add_i32 s49, s51, s30
	v_lshl_add_u64 v[226:227], s[0:1], 0, v[162:163]
	s_mov_b32 m0, s49
	ds_read_b128 v[194:197], v187 offset:16384
	ds_read_b128 v[198:201], v187 offset:17408
	ds_read_b128 v[202:205], v187 offset:18432
	ds_read_b128 v[206:209], v187 offset:19456
	ds_read_b128 v[210:213], v187 offset:20480
	ds_read_b128 v[214:217], v187 offset:21504
	ds_read_b128 v[218:221], v187 offset:22528
	ds_read_b128 v[222:225], v187 offset:23552
	global_load_lds_dwordx4 v[226:227], off
	s_add_i32 m0, s49, 0x2000
	s_add_u32 s50, s0, 0x30000
	v_lshl_add_u64 v[228:229], s[0:1], 0, v[166:167]
	s_addc_u32 s51, s1, 0
	s_add_i32 s49, s43, s30
	global_load_lds_dwordx4 v[228:229], off
	v_lshl_add_u64 v[2:3], s[50:51], 0, v[162:163]
	s_mov_b32 m0, s49
	v_lshl_add_u64 v[230:231], s[24:25], 0, v[160:161]
	global_load_lds_dwordx4 v[2:3], off
	v_lshl_add_u64 v[2:3], s[50:51], 0, v[166:167]
	s_add_i32 m0, s49, 0x2000
	v_lshl_add_u64 v[234:235], s[24:25], 0, v[164:165]
	global_load_lds_dwordx4 v[2:3], off
	s_mov_b32 m0, s31
	s_nop 0
	global_load_lds_dwordx4 v[230:231], off
	s_mov_b32 m0, s34
	s_nop 0
	global_load_lds_dwordx4 v[234:235], off
	s_waitcnt vmcnt(8)
	s_waitcnt lgkmcnt(0)
	s_barrier
	s_setprio 1
	s_waitcnt lgkmcnt(0)
	s_cmpk_eq_u32 s33, 0x80
	s_cbranch_scc1 .Lskiphalf_6
; #define PG8_STAGE(bufoff, gbase, voff) do { _Pragma("unroll") for (int _i = 0; _i < 2; ++_i) \
;         __builtin_amdgcn_global_load_lds((const unsigned*)((const char*)(gbase) + (voff)[_i]), (PG8_LAS unsigned*)(lds + (bufoff) + ldsw + _i * 8192), 16, 0, 0); } while (0)
; #define PG8_LDA(dst, b, h) do { _Pragma("unroll") for (int m = 0; m < 4; ++m) _Pragma("unroll") for (int k = 0; k < 2; ++k) dst[m][k] = *(const PG8_LAS bf16x8*)(lds + PG8_SA(b, h) + aoff + m * 2048 + k * 1024); } while (0)
; #define PG8_LDB(dst, b, h) do { _Pragma("unroll") for (int n = 0; n < 2; ++n) _Pragma("unroll") for (int k = 0; k < 2; ++k) dst[n][k] = *(const PG8_LAS bf16x8*)(lds + PG8_SB(b, h) + boff + n * 2048 + k * 1024); } while (0)
; #define PG8_MMA(ai, bj, At, Bt) do { __builtin_amdgcn_s_setprio(1); _Pragma("unroll") for (int m = 0; m < 4; ++m) _Pragma("unroll") for (int n = 0; n < 2; ++n) _Pragma("unroll") for (int k = 0; k < 2; ++k) \
;         acc[ai][bj][m][n] = __builtin_amdgcn_mfma_f32_16x16x32_bf16(Bt[n][k], At[m][k], acc[ai][bj][m][n], 0, 0, 0); __builtin_amdgcn_s_setprio(0); } while (0)
; #define PG8_WAIT_V(n) asm volatile("s_waitcnt vmcnt(" #n ")" ::: "memory")
; #define PG8_WAIT_L(n) asm volatile("s_waitcnt lgkmcnt(" #n ")" ::: "memory")
; #define PG8_BAR __builtin_amdgcn_s_barrier()
; #define PG8_SCHED __builtin_amdgcn_sched_barrier(0)
; template <class Epi, class Sched, bool ALIGN_EPI = false, bool SP2 = false, class Bg = BgNone>
; __device__ __forceinline__ void gemm_phase(PG8_LAS unsigned char* lds, const Gemm g, const Sched& S, const Epi& E, const int wave_sg, const Bg& bg = Bg()) {
;     ...
;             if (bg_on) { PG8_WAIT_V(10); } else { PG8_WAIT_V(8); } PG8_WAIT_L(0); PG8_BAR; PG8_MMA(1, 0, At, B0); PG8_MMA(1, 1, At, B1); PG8_BAR; PG8_SCHED;
;             PG8_LDB(B0, 1, 0); PG8_LDB(B1, 1, 1); PG8_SCHED; PG8_LDA(At, 1, 0); PG8_STAGE(PG8_SA(0, 1), a2 + hstep, voffA);
;             PG8_WAIT_V(8); PG8_WAIT_L(0); PG8_BAR; PG8_MMA(0, 0, At, B0); PG8_MMA(0, 1, At, B1); PG8_BAR; PG8_SCHED;
	v_mfma_f32_16x16x32_bf16 v[64:67], v[132:135], v[194:197], v[64:67]
	v_mfma_f32_16x16x32_bf16 v[60:63], v[140:143], v[194:197], v[60:63]
	v_mfma_f32_16x16x32_bf16 v[48:51], v[132:135], v[202:205], v[48:51]
	v_mfma_f32_16x16x32_bf16 v[44:47], v[140:143], v[202:205], v[44:47]
	v_mfma_f32_16x16x32_bf16 v[32:35], v[132:135], v[210:213], v[32:35]
	v_mfma_f32_16x16x32_bf16 v[28:31], v[140:143], v[210:213], v[28:31]
	v_mfma_f32_16x16x32_bf16 v[16:19], v[132:135], v[218:221], v[16:19]
	v_mfma_f32_16x16x32_bf16 v[12:15], v[140:143], v[218:221], v[12:15]
	v_mfma_f32_16x16x32_bf16 v[64:67], v[136:139], v[198:201], v[64:67]
	v_mfma_f32_16x16x32_bf16 v[60:63], v[144:147], v[198:201], v[60:63]
	v_mfma_f32_16x16x32_bf16 v[48:51], v[136:139], v[206:209], v[48:51]
	v_mfma_f32_16x16x32_bf16 v[44:47], v[144:147], v[206:209], v[44:47]
	v_mfma_f32_16x16x32_bf16 v[32:35], v[136:139], v[214:217], v[32:35]
	v_mfma_f32_16x16x32_bf16 v[28:31], v[144:147], v[214:217], v[28:31]
	v_mfma_f32_16x16x32_bf16 v[16:19], v[136:139], v[222:225], v[16:19]
	v_mfma_f32_16x16x32_bf16 v[12:15], v[144:147], v[222:225], v[12:15]
	s_setprio 0
	s_setprio 1
	v_mfma_f32_16x16x32_bf16 v[56:59], v[148:151], v[194:197], v[56:59]
	v_mfma_f32_16x16x32_bf16 v[52:55], v[156:159], v[194:197], v[52:55]
	v_mfma_f32_16x16x32_bf16 v[40:43], v[148:151], v[202:205], v[40:43]
	v_mfma_f32_16x16x32_bf16 v[36:39], v[156:159], v[202:205], v[36:39]
	v_mfma_f32_16x16x32_bf16 v[24:27], v[148:151], v[210:213], v[24:27]
	v_mfma_f32_16x16x32_bf16 v[20:23], v[156:159], v[210:213], v[20:23]
	v_mfma_f32_16x16x32_bf16 v[8:11], v[148:151], v[218:221], v[8:11]
	v_mfma_f32_16x16x32_bf16 v[2:5], v[156:159], v[218:221], v[4:7]
	v_mfma_f32_16x16x32_bf16 v[56:59], v[152:155], v[198:201], v[56:59]
	v_mfma_f32_16x16x32_bf16 v[52:55], v[190:193], v[198:201], v[52:55]
	v_mfma_f32_16x16x32_bf16 v[40:43], v[152:155], v[206:209], v[40:43]
	v_mfma_f32_16x16x32_bf16 v[36:39], v[190:193], v[206:209], v[36:39]
	v_mfma_f32_16x16x32_bf16 v[24:27], v[152:155], v[214:217], v[24:27]
	v_mfma_f32_16x16x32_bf16 v[20:23], v[190:193], v[214:217], v[20:23]
	v_mfma_f32_16x16x32_bf16 v[8:11], v[152:155], v[222:225], v[8:11]
	v_mfma_f32_16x16x32_bf16 v[2:5], v[190:193], v[222:225], v[2:5]
.Lskiphalf_6:
	s_setprio 0
	s_barrier
	s_add_i32 s49, 0, 0x18000
	v_add_u32_e32 v1, s49, v184
	s_add_i32 s50, 0, 0x1c000
	ds_read_b128 v[132:135], v1
	ds_read_b128 v[136:139], v1 offset:1024
	ds_read_b128 v[140:143], v1 offset:2048
	ds_read_b128 v[144:147], v1 offset:3072
	v_add_u32_e32 v1, s50, v184
	ds_read_b128 v[148:151], v1
	ds_read_b128 v[152:155], v1 offset:1024
	ds_read_b128 v[156:159], v1 offset:2048
	ds_read_b128 v[190:193], v1 offset:3072
	s_add_u32 s24, s24, 0x30000
	s_addc_u32 s25, s25, 0
	s_mov_b32 m0, s35
	v_lshl_add_u64 v[6:7], s[24:25], 0, v[160:161]
	ds_read_b128 v[194:197], v187 offset:32768
	ds_read_b128 v[198:201], v187 offset:33792
	ds_read_b128 v[202:205], v187 offset:34816
	ds_read_b128 v[206:209], v187 offset:35840
	ds_read_b128 v[210:213], v187 offset:36864
	ds_read_b128 v[214:217], v187 offset:37888
	ds_read_b128 v[218:221], v187 offset:38912
	ds_read_b128 v[222:225], v187 offset:39936
	global_load_lds_dwordx4 v[6:7], off
	v_lshl_add_u64 v[6:7], s[24:25], 0, v[164:165]
	s_mov_b32 m0, s36
	s_nop 0
	global_load_lds_dwordx4 v[6:7], off
	s_waitcnt vmcnt(8)
	s_waitcnt lgkmcnt(0)
	s_barrier
	s_setprio 1
	s_waitcnt lgkmcnt(0)
	v_mfma_f32_16x16x32_bf16 v[128:131], v[132:135], v[194:197], v[128:131]
	v_mfma_f32_16x16x32_bf16 v[124:127], v[140:143], v[194:197], v[124:127]
	v_mfma_f32_16x16x32_bf16 v[112:115], v[132:135], v[202:205], v[112:115]
	v_mfma_f32_16x16x32_bf16 v[108:111], v[140:143], v[202:205], v[108:111]
	v_mfma_f32_16x16x32_bf16 v[96:99], v[132:135], v[210:213], v[96:99]
	v_mfma_f32_16x16x32_bf16 v[92:95], v[140:143], v[210:213], v[92:95]
	v_mfma_f32_16x16x32_bf16 v[80:83], v[132:135], v[218:221], v[80:83]
	v_mfma_f32_16x16x32_bf16 v[76:79], v[140:143], v[218:221], v[76:79]
	v_mfma_f32_16x16x32_bf16 v[128:131], v[136:139], v[198:201], v[128:131]
	v_mfma_f32_16x16x32_bf16 v[124:127], v[144:147], v[198:201], v[124:127]
	v_mfma_f32_16x16x32_bf16 v[112:115], v[136:139], v[206:209], v[112:115]
	v_mfma_f32_16x16x32_bf16 v[108:111], v[144:147], v[206:209], v[108:111]
	v_mfma_f32_16x16x32_bf16 v[96:99], v[136:139], v[214:217], v[96:99]
	v_mfma_f32_16x16x32_bf16 v[92:95], v[144:147], v[214:217], v[92:95]
	v_mfma_f32_16x16x32_bf16 v[80:83], v[136:139], v[222:225], v[80:83]
	v_mfma_f32_16x16x32_bf16 v[76:79], v[144:147], v[222:225], v[76:79]
	s_setprio 0
	s_setprio 1
	v_mfma_f32_16x16x32_bf16 v[120:123], v[148:151], v[194:197], v[120:123]
	v_mfma_f32_16x16x32_bf16 v[116:119], v[156:159], v[194:197], v[116:119]
	v_mfma_f32_16x16x32_bf16 v[104:107], v[148:151], v[202:205], v[104:107]
	v_mfma_f32_16x16x32_bf16 v[100:103], v[156:159], v[202:205], v[100:103]
	v_mfma_f32_16x16x32_bf16 v[88:91], v[148:151], v[210:213], v[88:91]
	v_mfma_f32_16x16x32_bf16 v[84:87], v[156:159], v[210:213], v[84:87]
	v_mfma_f32_16x16x32_bf16 v[72:75], v[148:151], v[218:221], v[72:75]
	v_mfma_f32_16x16x32_bf16 v[68:71], v[156:159], v[218:221], v[68:71]
	v_mfma_f32_16x16x32_bf16 v[120:123], v[152:155], v[198:201], v[120:123]
	v_mfma_f32_16x16x32_bf16 v[116:119], v[190:193], v[198:201], v[116:119]
	v_mfma_f32_16x16x32_bf16 v[104:107], v[152:155], v[206:209], v[104:107]
	v_mfma_f32_16x16x32_bf16 v[100:103], v[190:193], v[206:209], v[100:103]
	v_mfma_f32_16x16x32_bf16 v[88:91], v[152:155], v[214:217], v[88:91]
	v_mfma_f32_16x16x32_bf16 v[84:87], v[190:193], v[214:217], v[84:87]
	v_mfma_f32_16x16x32_bf16 v[72:75], v[152:155], v[222:225], v[72:75]
	v_mfma_f32_16x16x32_bf16 v[68:71], v[190:193], v[222:225], v[68:71]
	s_setprio 0
	s_barrier
; #define PG8_STAGE(bufoff, gbase, voff) do { _Pragma("unroll") for (int _i = 0; _i < 2; ++_i) \
;         __builtin_amdgcn_global_load_lds((const unsigned*)((const char*)(gbase) + (voff)[_i]), (PG8_LAS unsigned*)(lds + (bufoff) + ldsw + _i * 8192), 16, 0, 0); } while (0)
; #define PG8_LDA(dst, b, h) do { _Pragma("unroll") for (int m = 0; m < 4; ++m) _Pragma("unroll") for (int k = 0; k < 2; ++k) dst[m][k] = *(const PG8_LAS bf16x8*)(lds + PG8_SA(b, h) + aoff + m * 2048 + k * 1024); } while (0)
; #define PG8_MMA(ai, bj, At, Bt) do { __builtin_amdgcn_s_setprio(1); _Pragma("unroll") for (int m = 0; m < 4; ++m) _Pragma("unroll") for (int n = 0; n < 2; ++n) _Pragma("unroll") for (int k = 0; k < 2; ++k) \
;         acc[ai][bj][m][n] = __builtin_amdgcn_mfma_f32_16x16x32_bf16(Bt[n][k], At[m][k], acc[ai][bj][m][n], 0, 0, 0); __builtin_amdgcn_s_setprio(0); } while (0)
; #define PG8_WAIT_V(n) asm volatile("s_waitcnt vmcnt(" #n ")" ::: "memory")
; #define PG8_WAIT_L(n) asm volatile("s_waitcnt lgkmcnt(" #n ")" ::: "memory")
; #define PG8_BAR __builtin_amdgcn_s_barrier()
; #define PG8_SCHED __builtin_amdgcn_sched_barrier(0)
; template <class Epi, class Sched, bool ALIGN_EPI = false, bool SP2 = false, class Bg = BgNone>
; __device__ __forceinline__ void gemm_phase(PG8_LAS unsigned char* lds, const Gemm g, const Sched& S, const Epi& E, const int wave_sg, const Bg& bg = Bg()) {
;     ...
;             PG8_LDA(At, 1, 1); PG8_STAGE(PG8_SB(1, 0), b3, voffB); PG8_STAGE(PG8_SB(1, 1), b3 + hstep, voffB); PG8_STAGE(PG8_SA(1, 0), a3, voffA);
;             PG8_WAIT_V(8); PG8_WAIT_L(0); PG8_BAR; PG8_MMA(1, 0, At, B0); PG8_MMA(1, 1, At, B1); PG8_BAR; PG8_SCHED;
	s_add_i32 s24, s49, s30
	v_lshl_add_u64 v[6:7], v[226:227], 0, s[18:19]
	s_mov_b32 m0, s24
	ds_read_b128 v[194:197], v187 offset:49152
	ds_read_b128 v[198:201], v187 offset:50176
	ds_read_b128 v[202:205], v187 offset:51200
	ds_read_b128 v[206:209], v187 offset:52224
	ds_read_b128 v[210:213], v187 offset:53248
	ds_read_b128 v[214:217], v187 offset:54272
	ds_read_b128 v[218:221], v187 offset:55296
	ds_read_b128 v[222:225], v187 offset:56320
	global_load_lds_dwordx4 v[6:7], off
	s_add_i32 m0, s24, 0x2000
	s_add_u32 s0, s0, 0x30080
	v_lshl_add_u64 v[6:7], v[228:229], 0, s[18:19]
	s_addc_u32 s1, s1, 0
	s_add_i32 s24, s50, s30
	global_load_lds_dwordx4 v[6:7], off
	v_lshl_add_u64 v[6:7], s[0:1], 0, v[162:163]
	s_mov_b32 m0, s24
	s_nop 0
	global_load_lds_dwordx4 v[6:7], off
	v_lshl_add_u64 v[6:7], s[0:1], 0, v[166:167]
	s_add_i32 m0, s24, 0x2000
	s_nop 0
	global_load_lds_dwordx4 v[6:7], off
	v_lshl_add_u64 v[6:7], v[230:231], 0, s[18:19]
	s_mov_b32 m0, s38
	s_nop 0
	global_load_lds_dwordx4 v[6:7], off
	v_lshl_add_u64 v[6:7], v[234:235], 0, s[18:19]
	s_mov_b32 m0, s39
	s_nop 0
	global_load_lds_dwordx4 v[6:7], off
	s_waitcnt vmcnt(8)
	s_waitcnt lgkmcnt(0)
	s_barrier
	s_setprio 1
	s_waitcnt lgkmcnt(0)
	s_cmpk_eq_u32 s33, 0x80
	s_cbranch_scc1 .Lskiphalf_7
	v_mfma_f32_16x16x32_bf16 v[64:67], v[132:135], v[194:197], v[64:67]
	v_mfma_f32_16x16x32_bf16 v[60:63], v[140:143], v[194:197], v[60:63]
	v_mfma_f32_16x16x32_bf16 v[48:51], v[132:135], v[202:205], v[48:51]
	v_mfma_f32_16x16x32_bf16 v[44:47], v[140:143], v[202:205], v[44:47]
	v_mfma_f32_16x16x32_bf16 v[32:35], v[132:135], v[210:213], v[32:35]
	v_mfma_f32_16x16x32_bf16 v[28:31], v[140:143], v[210:213], v[28:31]
	v_mfma_f32_16x16x32_bf16 v[16:19], v[132:135], v[218:221], v[16:19]
	v_mfma_f32_16x16x32_bf16 v[12:15], v[140:143], v[218:221], v[12:15]
	v_mfma_f32_16x16x32_bf16 v[64:67], v[136:139], v[198:201], v[64:67]
	v_mfma_f32_16x16x32_bf16 v[60:63], v[144:147], v[198:201], v[60:63]
	v_mfma_f32_16x16x32_bf16 v[48:51], v[136:139], v[206:209], v[48:51]
	v_mfma_f32_16x16x32_bf16 v[44:47], v[144:147], v[206:209], v[44:47]
	v_mfma_f32_16x16x32_bf16 v[32:35], v[136:139], v[214:217], v[32:35]
	v_mfma_f32_16x16x32_bf16 v[28:31], v[144:147], v[214:217], v[28:31]
	v_mfma_f32_16x16x32_bf16 v[16:19], v[136:139], v[222:225], v[16:19]
	v_mfma_f32_16x16x32_bf16 v[12:15], v[144:147], v[222:225], v[12:15]
	s_setprio 0
	s_setprio 1
	v_mfma_f32_16x16x32_bf16 v[56:59], v[148:151], v[194:197], v[56:59]
	v_mfma_f32_16x16x32_bf16 v[52:55], v[156:159], v[194:197], v[52:55]
	v_mfma_f32_16x16x32_bf16 v[40:43], v[148:151], v[202:205], v[40:43]
	v_mfma_f32_16x16x32_bf16 v[36:39], v[156:159], v[202:205], v[36:39]
	v_mfma_f32_16x16x32_bf16 v[24:27], v[148:151], v[210:213], v[24:27]
	v_mfma_f32_16x16x32_bf16 v[20:23], v[156:159], v[210:213], v[20:23]
	v_mfma_f32_16x16x32_bf16 v[6:9], v[148:151], v[218:221], v[8:11]
	v_mfma_f32_16x16x32_bf16 v[2:5], v[156:159], v[218:221], v[2:5]
	v_mfma_f32_16x16x32_bf16 v[56:59], v[152:155], v[198:201], v[56:59]
	v_mfma_f32_16x16x32_bf16 v[52:55], v[190:193], v[198:201], v[52:55]
	v_mfma_f32_16x16x32_bf16 v[40:43], v[152:155], v[206:209], v[40:43]
	v_mfma_f32_16x16x32_bf16 v[36:39], v[190:193], v[206:209], v[36:39]
	v_mfma_f32_16x16x32_bf16 v[24:27], v[152:155], v[214:217], v[24:27]
	v_mfma_f32_16x16x32_bf16 v[20:23], v[190:193], v[214:217], v[20:23]
	v_mfma_f32_16x16x32_bf16 v[8:11], v[152:155], v[222:225], v[6:9]
	v_mfma_f32_16x16x32_bf16 v[4:7], v[190:193], v[222:225], v[2:5]
.Lskiphalf_7:
	s_setprio 0
	s_barrier
	s_add_i32 s48, s48, 2
	s_add_u32 s6, s6, 0x100
	s_addc_u32 s7, s7, 0
	s_cmp_gt_u32 s48, 9
	s_cbranch_scc1 .LBB0_968

; #define PG8_STAGE(bufoff, gbase, voff) do { _Pragma("unroll") for (int _i = 0; _i < 2; ++_i) \
;         __builtin_amdgcn_global_load_lds((const unsigned*)((const char*)(gbase) + (voff)[_i]), (PG8_LAS unsigned*)(lds + (bufoff) + ldsw + _i * 8192), 16, 0, 0); } while (0)
; #define PG8_WAIT_V(n) asm volatile("s_waitcnt vmcnt(" #n ")" ::: "memory")
; template <class Epi, class Sched, bool ALIGN_EPI = false, bool SP2 = false, class Bg = BgNone>
; __device__ __forceinline__ void gemm_phase(PG8_LAS unsigned char* lds, const Gemm g, const Sched& S, const Epi& E, const int wave_sg, const Bg& bg = Bg()) {
;     ...
;             const bool last = (t == cnt_ - 2);
;             const char* a1 = cA + (size_t)(t + 1) * kstep;
;             const char* a2 = last ? nA : cA + (size_t)(t + 2) * kstep; const char* b2 = last ? nB : cB + (size_t)(t + 2) * kstep;
;             const char* a3 = a2 + kstep; const char* b3 = b2 + kstep;
;             if (last && has_next) S.a_ready(nxt);
;             if constexpr (SP2) {
;             bool bg_on = false;
;             if constexpr (Bg::PER != 0) { bg_on = ui < bg.rounds;
;                 if (bg_on) {
;                     const unsigned idx = bg.lo + (unsigned)((ui * (nt >> 1) + (t >> 1)) * (int)gridDim.x + (int)blockIdx.x) * 512u + (unsigned)tid; const bool ok = idx < bg.hi;
;                     const unsigned n = idx / Bg::PER, j = idx - n * Bg::PER; const size_t so = (size_t)n * Bg::LR4 + j;
;                     const f32x4* sp = ok ? bg.src + so + Bg::R4 : bg.src; f32x4* nd = ok ? bg.dst + so : bg.dump + (size_t)blockIdx.x * 512 + tid;
;                     asm volatile("global_store_dwordx4 %1, %0, off nt\n\tglobal_load_dwordx4 %0, %2, off nt" : "+v"(bgdata) : "v"(bgdst), "v"(sp) : "memory");
;                     bgdst = nd; } }
;             PG8_LDB(B0, 0, 0); PG8_LDB(B1, 0, 1); PG8_SCHED; PG8_LDA(At, 0, 0); PG8_STAGE(PG8_SA(1, 1), a1 + hstep, voffA);
;             if (bg_on) { PG8_WAIT_V(10); } else { PG8_WAIT_V(8); } PG8_WAIT_L(0); PG8_BAR; PG8_MMA(0, 0, At, B0); PG8_MMA(0, 1, At, B1); PG8_BAR; PG8_SCHED;
;             PG8_LDA(At, 0, 1); PG8_STAGE(PG8_SB(0, 0), b2, voffB); PG8_STAGE(PG8_SB(0, 1), b2 + hstep, voffB); PG8_STAGE(PG8_SA(0, 0), a2, voffA);
;             if (bg_on) { PG8_WAIT_V(10); } else { PG8_WAIT_V(8); } PG8_WAIT_L(0); PG8_BAR; PG8_MMA(1, 0, At, B0); PG8_MMA(1, 1, At, B1); PG8_BAR; PG8_SCHED;
.LBB0_1053:
	ds_read_b128 v[144:147], v167
	ds_read_b128 v[148:151], v167 offset:1024
	ds_read_b128 v[152:155], v167 offset:2048
	ds_read_b128 v[156:159], v167 offset:3072
	ds_read_b128 v[160:163], v168
	ds_read_b128 v[172:175], v168 offset:1024
	ds_read_b128 v[176:179], v168 offset:2048
	ds_read_b128 v[180:183], v168 offset:3072
	s_add_i32 s77, s4, 2
	s_add_u32 s5, s0, 0xfffc0080
	s_addc_u32 s6, s1, -1
	s_cmp_eq_u32 s45, s4
	s_cselect_b32 s4, s39, s48
	s_cselect_b32 s7, s33, s6
	s_cselect_b32 s6, s35, s5
	s_cselect_b32 s5, s37, s49
	v_lshl_add_u64 v[216:217], s[0:1], 0, v[134:135]
	s_add_i32 m0, s47, 0xc000
	ds_read_b128 v[184:187], v169
	ds_read_b128 v[188:191], v169 offset:1024
	ds_read_b128 v[192:195], v169 offset:2048
	ds_read_b128 v[196:199], v169 offset:3072
	ds_read_b128 v[200:203], v169 offset:4096
	ds_read_b128 v[204:207], v169 offset:5120
	ds_read_b128 v[208:211], v169 offset:6144
	ds_read_b128 v[212:215], v169 offset:7168
	global_load_lds_dwordx4 v[216:217], off
	v_lshl_add_u64 v[216:217], s[0:1], 0, v[136:137]
	s_add_i32 m0, s47, 0xe000
	s_nop 0
	global_load_lds_dwordx4 v[216:217], off
	s_waitcnt vmcnt(8)
	s_waitcnt lgkmcnt(0)
	s_barrier
	s_setprio 1
	s_waitcnt lgkmcnt(0)
	v_mfma_f32_16x16x32_bf16 v[64:67], v[144:147], v[184:187], v[64:67]
	v_mfma_f32_16x16x32_bf16 v[60:63], v[152:155], v[184:187], v[60:63]
	v_mfma_f32_16x16x32_bf16 v[48:51], v[144:147], v[192:195], v[48:51]
	v_mfma_f32_16x16x32_bf16 v[40:43], v[152:155], v[192:195], v[40:43]
	v_mfma_f32_16x16x32_bf16 v[32:35], v[144:147], v[200:203], v[32:35]
	v_mfma_f32_16x16x32_bf16 v[24:27], v[152:155], v[200:203], v[24:27]
	v_mfma_f32_16x16x32_bf16 v[16:19], v[144:147], v[208:211], v[16:19]
	v_mfma_f32_16x16x32_bf16 v[8:11], v[152:155], v[208:211], v[8:11]
	v_mfma_f32_16x16x32_bf16 v[64:67], v[148:151], v[188:191], v[64:67]
	v_mfma_f32_16x16x32_bf16 v[60:63], v[156:159], v[188:191], v[60:63]
	v_mfma_f32_16x16x32_bf16 v[48:51], v[148:151], v[196:199], v[48:51]
	v_mfma_f32_16x16x32_bf16 v[40:43], v[156:159], v[196:199], v[40:43]
	v_mfma_f32_16x16x32_bf16 v[32:35], v[148:151], v[204:207], v[32:35]
	v_mfma_f32_16x16x32_bf16 v[24:27], v[156:159], v[204:207], v[24:27]
	v_mfma_f32_16x16x32_bf16 v[16:19], v[148:151], v[212:215], v[16:19]
	v_mfma_f32_16x16x32_bf16 v[8:11], v[156:159], v[212:215], v[8:11]
	s_setprio 0
	s_setprio 1
	v_mfma_f32_16x16x32_bf16 v[52:55], v[160:163], v[184:187], v[52:55]
	v_mfma_f32_16x16x32_bf16 v[44:47], v[176:179], v[184:187], v[44:47]
	v_mfma_f32_16x16x32_bf16 v[36:39], v[160:163], v[192:195], v[36:39]
	v_mfma_f32_16x16x32_bf16 v[28:31], v[176:179], v[192:195], v[28:31]
	v_mfma_f32_16x16x32_bf16 v[20:23], v[160:163], v[200:203], v[20:23]
	v_mfma_f32_16x16x32_bf16 v[12:15], v[176:179], v[200:203], v[12:15]
	v_mfma_f32_16x16x32_bf16 v[4:7], v[160:163], v[208:211], v[4:7]
	v_mfma_f32_16x16x32_bf16 v[0:3], v[176:179], v[208:211], v[0:3]
	v_mfma_f32_16x16x32_bf16 v[52:55], v[172:175], v[188:191], v[52:55]
	v_mfma_f32_16x16x32_bf16 v[44:47], v[180:183], v[188:191], v[44:47]
	v_mfma_f32_16x16x32_bf16 v[36:39], v[172:175], v[196:199], v[36:39]
	v_mfma_f32_16x16x32_bf16 v[28:31], v[180:183], v[196:199], v[28:31]
	v_mfma_f32_16x16x32_bf16 v[20:23], v[172:175], v[204:207], v[20:23]
	v_mfma_f32_16x16x32_bf16 v[12:15], v[180:183], v[204:207], v[12:15]
	v_mfma_f32_16x16x32_bf16 v[4:7], v[172:175], v[212:215], v[4:7]
	v_mfma_f32_16x16x32_bf16 v[0:3], v[180:183], v[212:215], v[0:3]
	s_setprio 0
	s_barrier
	s_add_i32 s78, s67, s54
	v_lshl_add_u64 v[216:217], s[4:5], 0, v[128:129]
	s_mov_b32 m0, s78
	ds_read_b128 v[184:187], v169 offset:16384
	ds_read_b128 v[188:191], v169 offset:17408
	ds_read_b128 v[192:195], v169 offset:18432
	ds_read_b128 v[196:199], v169 offset:19456
	ds_read_b128 v[200:203], v169 offset:20480
	ds_read_b128 v[204:207], v169 offset:21504
	ds_read_b128 v[208:211], v169 offset:22528
	ds_read_b128 v[212:215], v169 offset:23552
	global_load_lds_dwordx4 v[216:217], off
	s_add_i32 m0, s78, 0x2000
	s_add_u32 s78, s4, 0x40000
	v_lshl_add_u64 v[218:219], s[4:5], 0, v[130:131]
	s_addc_u32 s79, s5, 0
	s_add_i32 s80, s68, s54
	global_load_lds_dwordx4 v[218:219], off
	v_lshl_add_u64 v[220:221], s[78:79], 0, v[128:129]
	s_mov_b32 m0, s80
	v_lshl_add_u64 v[222:223], s[6:7], 0, v[130:131]
	global_load_lds_dwordx4 v[220:221], off
	v_lshl_add_u64 v[220:221], s[78:79], 0, v[130:131]
	s_add_i32 m0, s80, 0x2000
	s_nop 0
	global_load_lds_dwordx4 v[220:221], off
	v_lshl_add_u64 v[220:221], s[6:7], 0, v[128:129]
	s_mov_b32 m0, s47
	s_nop 0
	global_load_lds_dwordx4 v[220:221], off
	s_mov_b32 m0, s55
	s_nop 0
	global_load_lds_dwordx4 v[222:223], off
	s_waitcnt vmcnt(8)
	s_waitcnt lgkmcnt(0)
	s_barrier
	s_setprio 1
	s_waitcnt lgkmcnt(0)
	s_cmpk_eq_u32 s46, 0x80
	s_cbranch_scc1 .Lskiphalf_8
	v_mfma_f32_16x16x32_bf16 v[124:127], v[144:147], v[184:187], v[124:127]
	v_mfma_f32_16x16x32_bf16 v[120:123], v[152:155], v[184:187], v[120:123]
	v_mfma_f32_16x16x32_bf16 v[108:111], v[144:147], v[192:195], v[108:111]
	v_mfma_f32_16x16x32_bf16 v[104:107], v[152:155], v[192:195], v[104:107]
	v_mfma_f32_16x16x32_bf16 v[92:95], v[144:147], v[200:203], v[92:95]
	v_mfma_f32_16x16x32_bf16 v[88:91], v[152:155], v[200:203], v[88:91]
	v_mfma_f32_16x16x32_bf16 v[76:79], v[144:147], v[208:211], v[76:79]
	v_mfma_f32_16x16x32_bf16 v[72:75], v[152:155], v[208:211], v[72:75]
	v_mfma_f32_16x16x32_bf16 v[124:127], v[148:151], v[188:191], v[124:127]
	v_mfma_f32_16x16x32_bf16 v[120:123], v[156:159], v[188:191], v[120:123]
	v_mfma_f32_16x16x32_bf16 v[108:111], v[148:151], v[196:199], v[108:111]
	v_mfma_f32_16x16x32_bf16 v[104:107], v[156:159], v[196:199], v[104:107]
	v_mfma_f32_16x16x32_bf16 v[92:95], v[148:151], v[204:207], v[92:95]
	v_mfma_f32_16x16x32_bf16 v[88:91], v[156:159], v[204:207], v[88:91]
	v_mfma_f32_16x16x32_bf16 v[76:79], v[148:151], v[212:215], v[76:79]
	v_mfma_f32_16x16x32_bf16 v[72:75], v[156:159], v[212:215], v[72:75]
	s_setprio 0
	s_setprio 1
	v_mfma_f32_16x16x32_bf16 v[116:119], v[160:163], v[184:187], v[116:119]
	v_mfma_f32_16x16x32_bf16 v[112:115], v[176:179], v[184:187], v[112:115]
	v_mfma_f32_16x16x32_bf16 v[100:103], v[160:163], v[192:195], v[100:103]
	v_mfma_f32_16x16x32_bf16 v[96:99], v[176:179], v[192:195], v[96:99]
	v_mfma_f32_16x16x32_bf16 v[84:87], v[160:163], v[200:203], v[84:87]
	v_mfma_f32_16x16x32_bf16 v[80:83], v[176:179], v[200:203], v[80:83]
	v_mfma_f32_16x16x32_bf16 v[68:71], v[160:163], v[208:211], v[68:71]
	v_mfma_f32_16x16x32_bf16 v[56:59], v[176:179], v[208:211], v[56:59]
	v_mfma_f32_16x16x32_bf16 v[116:119], v[172:175], v[188:191], v[116:119]
	v_mfma_f32_16x16x32_bf16 v[112:115], v[180:183], v[188:191], v[112:115]
	v_mfma_f32_16x16x32_bf16 v[100:103], v[172:175], v[196:199], v[100:103]
	v_mfma_f32_16x16x32_bf16 v[96:99], v[180:183], v[196:199], v[96:99]
	v_mfma_f32_16x16x32_bf16 v[84:87], v[172:175], v[204:207], v[84:87]
	v_mfma_f32_16x16x32_bf16 v[80:83], v[180:183], v[204:207], v[80:83]
	v_mfma_f32_16x16x32_bf16 v[68:71], v[172:175], v[212:215], v[68:71]
	v_mfma_f32_16x16x32_bf16 v[56:59], v[180:183], v[212:215], v[56:59]
; #define PG8_STAGE(bufoff, gbase, voff) do { _Pragma("unroll") for (int _i = 0; _i < 2; ++_i) \
;         __builtin_amdgcn_global_load_lds((const unsigned*)((const char*)(gbase) + (voff)[_i]), (PG8_LAS unsigned*)(lds + (bufoff) + ldsw + _i * 8192), 16, 0, 0); } while (0)
; #define PG8_LDA(dst, b, h) do { _Pragma("unroll") for (int m = 0; m < 4; ++m) _Pragma("unroll") for (int k = 0; k < 2; ++k) dst[m][k] = *(const PG8_LAS bf16x8*)(lds + PG8_SA(b, h) + aoff + m * 2048 + k * 1024); } while (0)
; #define PG8_LDB(dst, b, h) do { _Pragma("unroll") for (int n = 0; n < 2; ++n) _Pragma("unroll") for (int k = 0; k < 2; ++k) dst[n][k] = *(const PG8_LAS bf16x8*)(lds + PG8_SB(b, h) + boff + n * 2048 + k * 1024); } while (0)
; #define PG8_MMA(ai, bj, At, Bt) do { __builtin_amdgcn_s_setprio(1); _Pragma("unroll") for (int m = 0; m < 4; ++m) _Pragma("unroll") for (int n = 0; n < 2; ++n) _Pragma("unroll") for (int k = 0; k < 2; ++k) \
;         acc[ai][bj][m][n] = __builtin_amdgcn_mfma_f32_16x16x32_bf16(Bt[n][k], At[m][k], acc[ai][bj][m][n], 0, 0, 0); __builtin_amdgcn_s_setprio(0); } while (0)
; #define PG8_WAIT_V(n) asm volatile("s_waitcnt vmcnt(" #n ")" ::: "memory")
; #define PG8_WAIT_L(n) asm volatile("s_waitcnt lgkmcnt(" #n ")" ::: "memory")
; #define PG8_BAR __builtin_amdgcn_s_barrier()
; #define PG8_SCHED __builtin_amdgcn_sched_barrier(0)
; template <class Epi, class Sched, bool ALIGN_EPI = false, bool SP2 = false, class Bg = BgNone>
; __device__ __forceinline__ void gemm_phase(PG8_LAS unsigned char* lds, const Gemm g, const Sched& S, const Epi& E, const int wave_sg, const Bg& bg = Bg()) {
;     ...
;             PG8_LDB(B0, 1, 0); PG8_LDB(B1, 1, 1); PG8_SCHED; PG8_LDA(At, 1, 0); PG8_STAGE(PG8_SA(0, 1), a2 + hstep, voffA);
;             PG8_WAIT_V(8); PG8_WAIT_L(0); PG8_BAR; PG8_MMA(0, 0, At, B0); PG8_MMA(0, 1, At, B1); PG8_BAR; PG8_SCHED;
;             PG8_LDA(At, 1, 1); PG8_STAGE(PG8_SB(1, 0), b3, voffB); PG8_STAGE(PG8_SB(1, 1), b3 + hstep, voffB); PG8_STAGE(PG8_SA(1, 0), a3, voffA);
;             PG8_WAIT_V(8); PG8_WAIT_L(0); PG8_BAR; PG8_MMA(1, 0, At, B0); PG8_MMA(1, 1, At, B1); PG8_BAR; PG8_SCHED;
.Lskiphalf_8:
	s_setprio 0
	s_barrier
	s_add_i32 s78, 0, 0x18000
	s_add_i32 s79, 0, 0x1c000
	v_add_u32_e32 v156, s78, v165
	v_add_u32_e32 v171, s79, v165
	ds_read_b128 v[144:147], v156
	ds_read_b128 v[148:151], v156 offset:1024
	ds_read_b128 v[152:155], v156 offset:2048
	ds_read_b128 v[156:159], v156 offset:3072
	ds_read_b128 v[160:163], v171
	ds_read_b128 v[172:175], v171 offset:1024
	ds_read_b128 v[176:179], v171 offset:2048
	ds_read_b128 v[180:183], v171 offset:3072
	s_add_u32 s6, s6, 0x40000
	s_addc_u32 s7, s7, 0
	s_mov_b32 m0, s56
	v_lshl_add_u64 v[224:225], s[6:7], 0, v[128:129]
	ds_read_b128 v[184:187], v169 offset:32768
	ds_read_b128 v[188:191], v169 offset:33792
	ds_read_b128 v[192:195], v169 offset:34816
	ds_read_b128 v[196:199], v169 offset:35840
	ds_read_b128 v[200:203], v169 offset:36864
	ds_read_b128 v[204:207], v169 offset:37888
	ds_read_b128 v[208:211], v169 offset:38912
	ds_read_b128 v[212:215], v169 offset:39936
	global_load_lds_dwordx4 v[224:225], off
	v_lshl_add_u64 v[224:225], s[6:7], 0, v[130:131]
	s_mov_b32 m0, s57
	s_nop 0
	global_load_lds_dwordx4 v[224:225], off
	s_waitcnt vmcnt(8)
	s_waitcnt lgkmcnt(0)
	s_barrier
	s_setprio 1
	s_waitcnt lgkmcnt(0)
	v_mfma_f32_16x16x32_bf16 v[64:67], v[144:147], v[184:187], v[64:67]
	v_mfma_f32_16x16x32_bf16 v[60:63], v[152:155], v[184:187], v[60:63]
	v_mfma_f32_16x16x32_bf16 v[48:51], v[144:147], v[192:195], v[48:51]
	v_mfma_f32_16x16x32_bf16 v[40:43], v[152:155], v[192:195], v[40:43]
	v_mfma_f32_16x16x32_bf16 v[32:35], v[144:147], v[200:203], v[32:35]
	v_mfma_f32_16x16x32_bf16 v[24:27], v[152:155], v[200:203], v[24:27]
	v_mfma_f32_16x16x32_bf16 v[16:19], v[144:147], v[208:211], v[16:19]
	v_mfma_f32_16x16x32_bf16 v[8:11], v[152:155], v[208:211], v[8:11]
	v_mfma_f32_16x16x32_bf16 v[64:67], v[148:151], v[188:191], v[64:67]
	v_mfma_f32_16x16x32_bf16 v[60:63], v[156:159], v[188:191], v[60:63]
	v_mfma_f32_16x16x32_bf16 v[48:51], v[148:151], v[196:199], v[48:51]
	v_mfma_f32_16x16x32_bf16 v[40:43], v[156:159], v[196:199], v[40:43]
	v_mfma_f32_16x16x32_bf16 v[32:35], v[148:151], v[204:207], v[32:35]
	v_mfma_f32_16x16x32_bf16 v[24:27], v[156:159], v[204:207], v[24:27]
	v_mfma_f32_16x16x32_bf16 v[16:19], v[148:151], v[212:215], v[16:19]
	v_mfma_f32_16x16x32_bf16 v[8:11], v[156:159], v[212:215], v[8:11]
	s_setprio 0
	s_setprio 1
	v_mfma_f32_16x16x32_bf16 v[52:55], v[160:163], v[184:187], v[52:55]
	v_mfma_f32_16x16x32_bf16 v[44:47], v[176:179], v[184:187], v[44:47]
	v_mfma_f32_16x16x32_bf16 v[36:39], v[160:163], v[192:195], v[36:39]
	v_mfma_f32_16x16x32_bf16 v[28:31], v[176:179], v[192:195], v[28:31]
	v_mfma_f32_16x16x32_bf16 v[20:23], v[160:163], v[200:203], v[20:23]
	v_mfma_f32_16x16x32_bf16 v[12:15], v[176:179], v[200:203], v[12:15]
	v_mfma_f32_16x16x32_bf16 v[4:7], v[160:163], v[208:211], v[4:7]
	v_mfma_f32_16x16x32_bf16 v[0:3], v[176:179], v[208:211], v[0:3]
	v_mfma_f32_16x16x32_bf16 v[52:55], v[172:175], v[188:191], v[52:55]
	v_mfma_f32_16x16x32_bf16 v[44:47], v[180:183], v[188:191], v[44:47]
	v_mfma_f32_16x16x32_bf16 v[36:39], v[172:175], v[196:199], v[36:39]
	v_mfma_f32_16x16x32_bf16 v[28:31], v[180:183], v[196:199], v[28:31]
	v_mfma_f32_16x16x32_bf16 v[20:23], v[172:175], v[204:207], v[20:23]
	v_mfma_f32_16x16x32_bf16 v[12:15], v[180:183], v[204:207], v[12:15]
	v_mfma_f32_16x16x32_bf16 v[4:7], v[172:175], v[212:215], v[4:7]
	v_mfma_f32_16x16x32_bf16 v[0:3], v[180:183], v[212:215], v[0:3]
	s_setprio 0
	s_barrier
	s_add_i32 s6, s78, s54
	v_lshl_add_u64 v[216:217], v[216:217], 0, s[22:23]
	s_mov_b32 m0, s6
	ds_read_b128 v[184:187], v169 offset:49152
	ds_read_b128 v[188:191], v169 offset:50176
	ds_read_b128 v[192:195], v169 offset:51200
	ds_read_b128 v[196:199], v169 offset:52224
	ds_read_b128 v[200:203], v169 offset:53248
	ds_read_b128 v[204:207], v169 offset:54272
	ds_read_b128 v[208:211], v169 offset:55296
	ds_read_b128 v[212:215], v169 offset:56320
	global_load_lds_dwordx4 v[216:217], off
	s_add_i32 m0, s6, 0x2000
	s_add_u32 s4, s4, 0x40080
	v_lshl_add_u64 v[216:217], v[218:219], 0, s[22:23]
	s_addc_u32 s5, s5, 0
	s_add_i32 s6, s79, s54
	global_load_lds_dwordx4 v[216:217], off
	v_lshl_add_u64 v[216:217], s[4:5], 0, v[128:129]
	s_mov_b32 m0, s6
	s_nop 0
	global_load_lds_dwordx4 v[216:217], off
	v_lshl_add_u64 v[216:217], s[4:5], 0, v[130:131]
	s_add_i32 m0, s6, 0x2000
	s_nop 0
	global_load_lds_dwordx4 v[216:217], off
	v_lshl_add_u64 v[216:217], v[220:221], 0, s[22:23]
	s_mov_b32 m0, s61
	s_nop 0
	global_load_lds_dwordx4 v[216:217], off
	v_lshl_add_u64 v[216:217], v[222:223], 0, s[22:23]
	s_mov_b32 m0, s62
	s_nop 0
	global_load_lds_dwordx4 v[216:217], off
	s_waitcnt vmcnt(8)
	s_waitcnt lgkmcnt(0)
	s_barrier
	s_setprio 1
	s_waitcnt lgkmcnt(0)
	s_cmpk_eq_u32 s46, 0x80
	s_cbranch_scc1 .Lskiphalf_9
	v_mfma_f32_16x16x32_bf16 v[124:127], v[144:147], v[184:187], v[124:127]
	v_mfma_f32_16x16x32_bf16 v[120:123], v[152:155], v[184:187], v[120:123]
	v_mfma_f32_16x16x32_bf16 v[108:111], v[144:147], v[192:195], v[108:111]
	v_mfma_f32_16x16x32_bf16 v[104:107], v[152:155], v[192:195], v[104:107]
	v_mfma_f32_16x16x32_bf16 v[92:95], v[144:147], v[200:203], v[92:95]
	v_mfma_f32_16x16x32_bf16 v[88:91], v[152:155], v[200:203], v[88:91]
	v_mfma_f32_16x16x32_bf16 v[76:79], v[144:147], v[208:211], v[76:79]
	v_mfma_f32_16x16x32_bf16 v[72:75], v[152:155], v[208:211], v[72:75]
	v_mfma_f32_16x16x32_bf16 v[124:127], v[148:151], v[188:191], v[124:127]
	v_mfma_f32_16x16x32_bf16 v[120:123], v[156:159], v[188:191], v[120:123]
	v_mfma_f32_16x16x32_bf16 v[108:111], v[148:151], v[196:199], v[108:111]
	v_mfma_f32_16x16x32_bf16 v[104:107], v[156:159], v[196:199], v[104:107]
	v_mfma_f32_16x16x32_bf16 v[92:95], v[148:151], v[204:207], v[92:95]
	v_mfma_f32_16x16x32_bf16 v[88:91], v[156:159], v[204:207], v[88:91]
	v_mfma_f32_16x16x32_bf16 v[76:79], v[148:151], v[212:215], v[76:79]
	v_mfma_f32_16x16x32_bf16 v[72:75], v[156:159], v[212:215], v[72:75]
	s_setprio 0
	s_setprio 1
	v_mfma_f32_16x16x32_bf16 v[116:119], v[160:163], v[184:187], v[116:119]
	v_mfma_f32_16x16x32_bf16 v[112:115], v[176:179], v[184:187], v[112:115]
	v_mfma_f32_16x16x32_bf16 v[100:103], v[160:163], v[192:195], v[100:103]
	v_mfma_f32_16x16x32_bf16 v[96:99], v[176:179], v[192:195], v[96:99]
	v_mfma_f32_16x16x32_bf16 v[84:87], v[160:163], v[200:203], v[84:87]
	v_mfma_f32_16x16x32_bf16 v[80:83], v[176:179], v[200:203], v[80:83]
	v_mfma_f32_16x16x32_bf16 v[68:71], v[160:163], v[208:211], v[68:71]
	v_mfma_f32_16x16x32_bf16 v[56:59], v[176:179], v[208:211], v[56:59]
	v_mfma_f32_16x16x32_bf16 v[116:119], v[172:175], v[188:191], v[116:119]
	v_mfma_f32_16x16x32_bf16 v[112:115], v[180:183], v[188:191], v[112:115]
	v_mfma_f32_16x16x32_bf16 v[100:103], v[172:175], v[196:199], v[100:103]
	v_mfma_f32_16x16x32_bf16 v[96:99], v[180:183], v[196:199], v[96:99]
	v_mfma_f32_16x16x32_bf16 v[84:87], v[172:175], v[204:207], v[84:87]
	v_mfma_f32_16x16x32_bf16 v[80:83], v[180:183], v[204:207], v[80:83]
	v_mfma_f32_16x16x32_bf16 v[68:71], v[172:175], v[212:215], v[68:71]
	v_mfma_f32_16x16x32_bf16 v[56:59], v[180:183], v[212:215], v[56:59]
; #define PG8_BAR __builtin_amdgcn_s_barrier()
; template <class Epi, class Sched, bool ALIGN_EPI = false, bool SP2 = false, class Bg = BgNone>
; __device__ __forceinline__ void gemm_phase(PG8_LAS unsigned char* lds, const Gemm g, const Sched& S, const Epi& E, const int wave_sg, const Bg& bg = Bg()) {
;     ...
;         for (int t = 0; t < cnt_; t += 2) {
;             if constexpr (Epi::HOOK_T >= 0) { if (t == Epi::HOOK_T) E.hook(acc, cur, wr, wc, fr, fq); }
;             const bool last = (t == cnt_ - 2);
;             const char* a1 = cA + (size_t)(t + 1) * kstep;
;             const char* a2 = last ? nA : cA + (size_t)(t + 2) * kstep; const char* b2 = last ? nB : cB + (size_t)(t + 2) * kstep;
;             const char* a3 = a2 + kstep; const char* b3 = b2 + kstep;
;     ...
;         }
;         if constexpr (ALIGN_EPI) { if (wr == 0) PG8_BAR; }
.Lskiphalf_9:
	s_setprio 0
	s_barrier
	s_add_u32 s0, s0, 0x100
	s_addc_u32 s1, s1, 0
	s_add_u32 s48, s48, 0x100
	s_addc_u32 s49, s49, 0
	s_cmp_ge_i32 s77, s3
	s_mov_b32 s4, s77
	s_cbranch_scc0 .LBB0_1053
	s_and_b64 vcc, exec, s[24:25]
	s_cbranch_vccz .LBB0_1056
	s_barrier

; #define PG8_STAGE(bufoff, gbase, voff) do { _Pragma("unroll") for (int _i = 0; _i < 2; ++_i) \
;         __builtin_amdgcn_global_load_lds((const unsigned*)((const char*)(gbase) + (voff)[_i]), (PG8_LAS unsigned*)(lds + (bufoff) + ldsw + _i * 8192), 16, 0, 0); } while (0)
; #define PG8_LDA(dst, b, h) do { _Pragma("unroll") for (int m = 0; m < 4; ++m) _Pragma("unroll") for (int k = 0; k < 2; ++k) dst[m][k] = *(const PG8_LAS bf16x8*)(lds + PG8_SA(b, h) + aoff + m * 2048 + k * 1024); } while (0)
; #define PG8_LDB(dst, b, h) do { _Pragma("unroll") for (int n = 0; n < 2; ++n) _Pragma("unroll") for (int k = 0; k < 2; ++k) dst[n][k] = *(const PG8_LAS bf16x8*)(lds + PG8_SB(b, h) + boff + n * 2048 + k * 1024); } while (0)
; #define PG8_MMA(ai, bj, At, Bt) do { __builtin_amdgcn_s_setprio(1); _Pragma("unroll") for (int m = 0; m < 4; ++m) _Pragma("unroll") for (int n = 0; n < 2; ++n) _Pragma("unroll") for (int k = 0; k < 2; ++k) \
;         acc[ai][bj][m][n] = __builtin_amdgcn_mfma_f32_16x16x32_bf16(Bt[n][k], At[m][k], acc[ai][bj][m][n], 0, 0, 0); __builtin_amdgcn_s_setprio(0); } while (0)
; #define PG8_WAIT_V(n) asm volatile("s_waitcnt vmcnt(" #n ")" ::: "memory")
; #define PG8_WAIT_L(n) asm volatile("s_waitcnt lgkmcnt(" #n ")" ::: "memory")
; #define PG8_BAR __builtin_amdgcn_s_barrier()
; #define PG8_SCHED __builtin_amdgcn_sched_barrier(0)
; template <class Epi, class Sched, bool ALIGN_EPI = false, bool SP2 = false, class Bg = BgNone>
; __device__ __forceinline__ void gemm_phase(PG8_LAS unsigned char* lds, const Gemm g, const Sched& S, const Epi& E, const int wave_sg, const Bg& bg = Bg()) {
;     ...
;             if (bg_on) { PG8_WAIT_V(10); } else { PG8_WAIT_V(8); } PG8_WAIT_L(0); PG8_BAR; PG8_MMA(1, 0, At, B0); PG8_MMA(1, 1, At, B1); PG8_BAR; PG8_SCHED;
;             PG8_LDB(B0, 1, 0); PG8_LDB(B1, 1, 1); PG8_SCHED; PG8_LDA(At, 1, 0); PG8_STAGE(PG8_SA(0, 1), a2 + hstep, voffA);
;             PG8_WAIT_V(8); PG8_WAIT_L(0); PG8_BAR; PG8_MMA(0, 0, At, B0); PG8_MMA(0, 1, At, B1); PG8_BAR; PG8_SCHED;
.LBB0_1184:
	s_waitcnt lgkmcnt(0)
	s_barrier
	s_setprio 1
	s_waitcnt lgkmcnt(0)
	s_cmpk_eq_u32 s34, 0x80
	s_cbranch_scc1 .Lskiphalf_10
	v_mfma_f32_16x16x32_bf16 v[62:65], v[150:153], v[190:193], v[62:65]
	v_mfma_f32_16x16x32_bf16 v[58:61], v[158:161], v[190:193], v[58:61]
	v_mfma_f32_16x16x32_bf16 v[46:49], v[150:153], v[182:185], v[46:49]
	v_mfma_f32_16x16x32_bf16 v[42:45], v[158:161], v[182:185], v[42:45]
	v_mfma_f32_16x16x32_bf16 v[30:33], v[150:153], v[174:177], v[30:33]
	v_mfma_f32_16x16x32_bf16 v[26:29], v[158:161], v[174:177], v[26:29]
	v_mfma_f32_16x16x32_bf16 v[14:17], v[150:153], v[166:169], v[14:17]
	v_mfma_f32_16x16x32_bf16 v[10:13], v[158:161], v[166:169], v[10:13]
	v_mfma_f32_16x16x32_bf16 v[62:65], v[154:157], v[194:197], v[62:65]
	v_mfma_f32_16x16x32_bf16 v[58:61], v[162:165], v[194:197], v[58:61]
	v_mfma_f32_16x16x32_bf16 v[46:49], v[154:157], v[186:189], v[46:49]
	v_mfma_f32_16x16x32_bf16 v[42:45], v[162:165], v[186:189], v[42:45]
	v_mfma_f32_16x16x32_bf16 v[30:33], v[154:157], v[178:181], v[30:33]
	v_mfma_f32_16x16x32_bf16 v[26:29], v[162:165], v[178:181], v[26:29]
	v_mfma_f32_16x16x32_bf16 v[14:17], v[154:157], v[170:173], v[14:17]
	v_mfma_f32_16x16x32_bf16 v[10:13], v[162:165], v[170:173], v[10:13]
	s_setprio 0
	s_setprio 1
	v_mfma_f32_16x16x32_bf16 v[66:69], v[134:137], v[190:193], v[66:69]
	v_mfma_f32_16x16x32_bf16 v[54:57], v[142:145], v[190:193], v[54:57]
	v_mfma_f32_16x16x32_bf16 v[50:53], v[134:137], v[182:185], v[50:53]
	v_mfma_f32_16x16x32_bf16 v[38:41], v[142:145], v[182:185], v[38:41]
	v_mfma_f32_16x16x32_bf16 v[34:37], v[134:137], v[174:177], v[34:37]
	v_mfma_f32_16x16x32_bf16 v[22:25], v[142:145], v[174:177], v[22:25]
	v_mfma_f32_16x16x32_bf16 v[18:21], v[134:137], v[166:169], v[18:21]
	v_mfma_f32_16x16x32_bf16 v[6:9], v[142:145], v[166:169], v[6:9]
	v_mfma_f32_16x16x32_bf16 v[66:69], v[138:141], v[194:197], v[66:69]
	v_mfma_f32_16x16x32_bf16 v[54:57], v[146:149], v[194:197], v[54:57]
	v_mfma_f32_16x16x32_bf16 v[50:53], v[138:141], v[186:189], v[50:53]
	v_mfma_f32_16x16x32_bf16 v[38:41], v[146:149], v[186:189], v[38:41]
	v_mfma_f32_16x16x32_bf16 v[34:37], v[138:141], v[178:181], v[34:37]
	v_mfma_f32_16x16x32_bf16 v[22:25], v[146:149], v[178:181], v[22:25]
	v_mfma_f32_16x16x32_bf16 v[18:21], v[138:141], v[170:173], v[18:21]
	v_mfma_f32_16x16x32_bf16 v[6:9], v[146:149], v[170:173], v[6:9]
.Lskiphalf_10:
	s_setprio 0
	s_barrier
	s_add_i32 s46, 0, 0x18000
	v_add_u32_e32 v0, s46, v233
	s_add_i32 s47, 0, 0x1c000
	ds_read_b128 v[134:137], v0
	ds_read_b128 v[138:141], v0 offset:1024
	ds_read_b128 v[142:145], v0 offset:2048
	ds_read_b128 v[146:149], v0 offset:3072
	v_add_u32_e32 v0, s47, v233
	ds_read_b128 v[150:153], v0
	ds_read_b128 v[154:157], v0 offset:1024
	ds_read_b128 v[158:161], v0 offset:2048
	ds_read_b128 v[162:165], v0 offset:3072
	s_add_u32 s44, s44, 0x40000
	s_addc_u32 s45, s45, 0
	s_mov_b32 m0, s55
	v_lshl_add_u64 v[240:241], s[44:45], 0, v[198:199]
	ds_read_b128 v[166:169], v237 offset:32768
	ds_read_b128 v[170:173], v237 offset:33792
	ds_read_b128 v[174:177], v237 offset:34816
	ds_read_b128 v[178:181], v237 offset:35840
	ds_read_b128 v[182:185], v237 offset:36864
	ds_read_b128 v[186:189], v237 offset:37888
	ds_read_b128 v[190:193], v237 offset:38912
	ds_read_b128 v[194:197], v237 offset:39936
	global_load_lds_dwordx4 v[240:241], off
	v_lshl_add_u64 v[240:241], s[44:45], 0, v[202:203]
	s_mov_b32 m0, s56
	s_nop 0
	global_load_lds_dwordx4 v[240:241], off
	s_waitcnt vmcnt(8)
	s_waitcnt lgkmcnt(0)
	s_barrier
	s_setprio 1
	s_waitcnt lgkmcnt(0)
	v_mfma_f32_16x16x32_bf16 v[126:129], v[134:137], v[166:169], v[126:129]
	v_mfma_f32_16x16x32_bf16 v[118:121], v[142:145], v[166:169], v[118:121]
	v_mfma_f32_16x16x32_bf16 v[110:113], v[134:137], v[174:177], v[110:113]
	v_mfma_f32_16x16x32_bf16 v[102:105], v[142:145], v[174:177], v[102:105]
	v_mfma_f32_16x16x32_bf16 v[94:97], v[134:137], v[182:185], v[94:97]
	v_mfma_f32_16x16x32_bf16 v[86:89], v[142:145], v[182:185], v[86:89]
	v_mfma_f32_16x16x32_bf16 v[78:81], v[134:137], v[190:193], v[78:81]
	v_mfma_f32_16x16x32_bf16 v[74:77], v[142:145], v[190:193], v[74:77]
	v_mfma_f32_16x16x32_bf16 v[126:129], v[138:141], v[170:173], v[126:129]
	v_mfma_f32_16x16x32_bf16 v[118:121], v[146:149], v[170:173], v[118:121]
	v_mfma_f32_16x16x32_bf16 v[110:113], v[138:141], v[178:181], v[110:113]
	v_mfma_f32_16x16x32_bf16 v[102:105], v[146:149], v[178:181], v[102:105]
	v_mfma_f32_16x16x32_bf16 v[94:97], v[138:141], v[186:189], v[94:97]
	v_mfma_f32_16x16x32_bf16 v[86:89], v[146:149], v[186:189], v[86:89]
	v_mfma_f32_16x16x32_bf16 v[78:81], v[138:141], v[194:197], v[78:81]
	v_mfma_f32_16x16x32_bf16 v[74:77], v[146:149], v[194:197], v[74:77]
	s_setprio 0
	s_setprio 1
	v_mfma_f32_16x16x32_bf16 v[130:133], v[150:153], v[166:169], v[130:133]
	v_mfma_f32_16x16x32_bf16 v[122:125], v[158:161], v[166:169], v[122:125]
	v_mfma_f32_16x16x32_bf16 v[114:117], v[150:153], v[174:177], v[114:117]
	v_mfma_f32_16x16x32_bf16 v[106:109], v[158:161], v[174:177], v[106:109]
	v_mfma_f32_16x16x32_bf16 v[98:101], v[150:153], v[182:185], v[98:101]
	v_mfma_f32_16x16x32_bf16 v[90:93], v[158:161], v[182:185], v[90:93]
	v_mfma_f32_16x16x32_bf16 v[82:85], v[150:153], v[190:193], v[82:85]
	v_mfma_f32_16x16x32_bf16 v[70:73], v[158:161], v[190:193], v[70:73]
	v_mfma_f32_16x16x32_bf16 v[130:133], v[154:157], v[170:173], v[130:133]
	v_mfma_f32_16x16x32_bf16 v[122:125], v[162:165], v[170:173], v[122:125]
	v_mfma_f32_16x16x32_bf16 v[114:117], v[154:157], v[178:181], v[114:117]
	v_mfma_f32_16x16x32_bf16 v[106:109], v[162:165], v[178:181], v[106:109]
	v_mfma_f32_16x16x32_bf16 v[98:101], v[154:157], v[186:189], v[98:101]
	v_mfma_f32_16x16x32_bf16 v[90:93], v[162:165], v[186:189], v[90:93]
	v_mfma_f32_16x16x32_bf16 v[82:85], v[154:157], v[194:197], v[82:85]
	v_mfma_f32_16x16x32_bf16 v[70:73], v[162:165], v[194:197], v[70:73]
	s_setprio 0
	s_barrier
; #define PG8_STAGE(bufoff, gbase, voff) do { _Pragma("unroll") for (int _i = 0; _i < 2; ++_i) \
;         __builtin_amdgcn_global_load_lds((const unsigned*)((const char*)(gbase) + (voff)[_i]), (PG8_LAS unsigned*)(lds + (bufoff) + ldsw + _i * 8192), 16, 0, 0); } while (0)
; #define PG8_LDA(dst, b, h) do { _Pragma("unroll") for (int m = 0; m < 4; ++m) _Pragma("unroll") for (int k = 0; k < 2; ++k) dst[m][k] = *(const PG8_LAS bf16x8*)(lds + PG8_SA(b, h) + aoff + m * 2048 + k * 1024); } while (0)
; #define PG8_MMA(ai, bj, At, Bt) do { __builtin_amdgcn_s_setprio(1); _Pragma("unroll") for (int m = 0; m < 4; ++m) _Pragma("unroll") for (int n = 0; n < 2; ++n) _Pragma("unroll") for (int k = 0; k < 2; ++k) \
;         acc[ai][bj][m][n] = __builtin_amdgcn_mfma_f32_16x16x32_bf16(Bt[n][k], At[m][k], acc[ai][bj][m][n], 0, 0, 0); __builtin_amdgcn_s_setprio(0); } while (0)
; #define PG8_WAIT_V(n) asm volatile("s_waitcnt vmcnt(" #n ")" ::: "memory")
; #define PG8_WAIT_L(n) asm volatile("s_waitcnt lgkmcnt(" #n ")" ::: "memory")
; #define PG8_BAR __builtin_amdgcn_s_barrier()
; #define PG8_SCHED __builtin_amdgcn_sched_barrier(0)
; template <class Epi, class Sched, bool ALIGN_EPI = false, bool SP2 = false, class Bg = BgNone>
; __device__ __forceinline__ void gemm_phase(PG8_LAS unsigned char* lds, const Gemm g, const Sched& S, const Epi& E, const int wave_sg, const Bg& bg = Bg()) {
;     ...
;             PG8_LDA(At, 1, 1); PG8_STAGE(PG8_SB(1, 0), b3, voffB); PG8_STAGE(PG8_SB(1, 1), b3 + hstep, voffB); PG8_STAGE(PG8_SA(1, 0), a3, voffA);
;             PG8_WAIT_V(8); PG8_WAIT_L(0); PG8_BAR; PG8_MMA(1, 0, At, B0); PG8_MMA(1, 1, At, B1); PG8_BAR; PG8_SCHED;
	s_add_i32 s44, s46, s50
	v_lshl_add_u64 v[230:231], v[230:231], 0, s[10:11]
	s_mov_b32 m0, s44
	ds_read_b128 v[166:169], v237 offset:49152
	ds_read_b128 v[170:173], v237 offset:50176
	ds_read_b128 v[174:177], v237 offset:51200
	ds_read_b128 v[178:181], v237 offset:52224
	ds_read_b128 v[182:185], v237 offset:53248
	ds_read_b128 v[186:189], v237 offset:54272
	ds_read_b128 v[190:193], v237 offset:55296
	ds_read_b128 v[194:197], v237 offset:56320
	global_load_lds_dwordx4 v[230:231], off
	s_add_i32 m0, s44, 0x2000
	s_add_u32 s42, s42, 0x40080
	v_lshl_add_u64 v[228:229], v[228:229], 0, s[10:11]
	s_addc_u32 s43, s43, 0
	s_add_i32 s44, s47, s50
	global_load_lds_dwordx4 v[228:229], off
	v_lshl_add_u64 v[228:229], s[42:43], 0, v[200:201]
	s_mov_b32 m0, s44
	v_lshl_add_u64 v[224:225], v[224:225], 0, s[10:11]
	global_load_lds_dwordx4 v[228:229], off
	v_lshl_add_u64 v[228:229], s[42:43], 0, v[204:205]
	s_add_i32 m0, s44, 0x2000
	s_nop 0
	global_load_lds_dwordx4 v[228:229], off
	s_mov_b32 m0, s57
	s_nop 0
	global_load_lds_dwordx4 v[224:225], off
	v_lshl_add_u64 v[224:225], v[226:227], 0, s[10:11]
	s_mov_b32 m0, s58
	s_nop 0
	global_load_lds_dwordx4 v[224:225], off
	s_waitcnt vmcnt(8)
	s_waitcnt lgkmcnt(0)
	s_barrier
	s_setprio 1
	s_waitcnt lgkmcnt(0)
	s_cmpk_eq_u32 s34, 0x80
	s_cbranch_scc1 .Lskiphalf_11
	v_mfma_f32_16x16x32_bf16 v[62:65], v[134:137], v[166:169], v[62:65]
	v_mfma_f32_16x16x32_bf16 v[58:61], v[142:145], v[166:169], v[58:61]
	v_mfma_f32_16x16x32_bf16 v[46:49], v[134:137], v[174:177], v[46:49]
	v_mfma_f32_16x16x32_bf16 v[42:45], v[142:145], v[174:177], v[42:45]
	v_mfma_f32_16x16x32_bf16 v[30:33], v[134:137], v[182:185], v[30:33]
	v_mfma_f32_16x16x32_bf16 v[26:29], v[142:145], v[182:185], v[26:29]
	v_mfma_f32_16x16x32_bf16 v[14:17], v[134:137], v[190:193], v[14:17]
	v_mfma_f32_16x16x32_bf16 v[10:13], v[142:145], v[190:193], v[10:13]
	v_mfma_f32_16x16x32_bf16 v[62:65], v[138:141], v[170:173], v[62:65]
	v_mfma_f32_16x16x32_bf16 v[58:61], v[146:149], v[170:173], v[58:61]
	v_mfma_f32_16x16x32_bf16 v[46:49], v[138:141], v[178:181], v[46:49]
	v_mfma_f32_16x16x32_bf16 v[42:45], v[146:149], v[178:181], v[42:45]
	v_mfma_f32_16x16x32_bf16 v[30:33], v[138:141], v[186:189], v[30:33]
	v_mfma_f32_16x16x32_bf16 v[26:29], v[146:149], v[186:189], v[26:29]
	v_mfma_f32_16x16x32_bf16 v[14:17], v[138:141], v[194:197], v[14:17]
	v_mfma_f32_16x16x32_bf16 v[10:13], v[146:149], v[194:197], v[10:13]
	s_setprio 0
	s_setprio 1
	v_mfma_f32_16x16x32_bf16 v[66:69], v[150:153], v[166:169], v[66:69]
	v_mfma_f32_16x16x32_bf16 v[54:57], v[158:161], v[166:169], v[54:57]
	v_mfma_f32_16x16x32_bf16 v[50:53], v[150:153], v[174:177], v[50:53]
	v_mfma_f32_16x16x32_bf16 v[38:41], v[158:161], v[174:177], v[38:41]
	v_mfma_f32_16x16x32_bf16 v[34:37], v[150:153], v[182:185], v[34:37]
	v_mfma_f32_16x16x32_bf16 v[22:25], v[158:161], v[182:185], v[22:25]
	v_mfma_f32_16x16x32_bf16 v[18:21], v[150:153], v[190:193], v[18:21]
	v_mfma_f32_16x16x32_bf16 v[6:9], v[158:161], v[190:193], v[6:9]
	v_mfma_f32_16x16x32_bf16 v[66:69], v[154:157], v[170:173], v[66:69]
	v_mfma_f32_16x16x32_bf16 v[54:57], v[162:165], v[170:173], v[54:57]
	v_mfma_f32_16x16x32_bf16 v[50:53], v[154:157], v[178:181], v[50:53]
	v_mfma_f32_16x16x32_bf16 v[38:41], v[162:165], v[178:181], v[38:41]
	v_mfma_f32_16x16x32_bf16 v[34:37], v[154:157], v[186:189], v[34:37]
	v_mfma_f32_16x16x32_bf16 v[22:25], v[162:165], v[186:189], v[22:25]
	v_mfma_f32_16x16x32_bf16 v[18:21], v[154:157], v[194:197], v[18:21]
	v_mfma_f32_16x16x32_bf16 v[6:9], v[162:165], v[194:197], v[6:9]
.Lskiphalf_11:
	s_setprio 0
	s_barrier
	s_add_i32 s74, s74, 2
	s_add_u32 s40, s40, 0x100
	s_addc_u32 s41, s41, 0
	s_cmp_gt_u32 s74, 13
	v_add_u32_e32 v238, s63, v238
	s_cbranch_scc1 .LBB0_1195

; #define PG8_STAGE(bufoff, gbase, voff) do { _Pragma("unroll") for (int _i = 0; _i < 2; ++_i) \
;         __builtin_amdgcn_global_load_lds((const unsigned*)((const char*)(gbase) + (voff)[_i]), (PG8_LAS unsigned*)(lds + (bufoff) + ldsw + _i * 8192), 16, 0, 0); } while (0)
; #define PG8_LDA(dst, b, h) do { _Pragma("unroll") for (int m = 0; m < 4; ++m) _Pragma("unroll") for (int k = 0; k < 2; ++k) dst[m][k] = *(const PG8_LAS bf16x8*)(lds + PG8_SA(b, h) + aoff + m * 2048 + k * 1024); } while (0)
; #define PG8_LDB(dst, b, h) do { _Pragma("unroll") for (int n = 0; n < 2; ++n) _Pragma("unroll") for (int k = 0; k < 2; ++k) dst[n][k] = *(const PG8_LAS bf16x8*)(lds + PG8_SB(b, h) + boff + n * 2048 + k * 1024); } while (0)
; #define PG8_MMA(ai, bj, At, Bt) do { __builtin_amdgcn_s_setprio(1); _Pragma("unroll") for (int m = 0; m < 4; ++m) _Pragma("unroll") for (int n = 0; n < 2; ++n) _Pragma("unroll") for (int k = 0; k < 2; ++k) \
;         acc[ai][bj][m][n] = __builtin_amdgcn_mfma_f32_16x16x32_bf16(Bt[n][k], At[m][k], acc[ai][bj][m][n], 0, 0, 0); __builtin_amdgcn_s_setprio(0); } while (0)
; #define PG8_WAIT_V(n) asm volatile("s_waitcnt vmcnt(" #n ")" ::: "memory")
; #define PG8_WAIT_L(n) asm volatile("s_waitcnt lgkmcnt(" #n ")" ::: "memory")
; #define PG8_BAR __builtin_amdgcn_s_barrier()
; #define PG8_SCHED __builtin_amdgcn_sched_barrier(0)
; template <class Epi, class Sched, bool ALIGN_EPI = false, bool SP2 = false, class Bg = BgNone>
; __device__ __forceinline__ void gemm_phase(PG8_LAS unsigned char* lds, const Gemm g, const Sched& S, const Epi& E, const int wave_sg, const Bg& bg = Bg()) {
;     ...
;             if (bg_on) { PG8_WAIT_V(10); } else { PG8_WAIT_V(8); } PG8_WAIT_L(0); PG8_BAR; PG8_MMA(1, 0, At, B0); PG8_MMA(1, 1, At, B1); PG8_BAR; PG8_SCHED;
;             PG8_LDB(B0, 1, 0); PG8_LDB(B1, 1, 1); PG8_SCHED; PG8_LDA(At, 1, 0); PG8_STAGE(PG8_SA(0, 1), a2 + hstep, voffA);
;             PG8_WAIT_V(8); PG8_WAIT_L(0); PG8_BAR; PG8_MMA(0, 0, At, B0); PG8_MMA(0, 1, At, B1); PG8_BAR; PG8_SCHED;
.LBB0_1281:
	s_waitcnt lgkmcnt(0)
	s_add_i32 s97, s97, 2
	s_barrier
	s_setprio 1
	s_waitcnt lgkmcnt(0)
	s_cmpk_eq_u32 s93, 0x80
	s_cbranch_scc1 .Lskiphalf_12
	v_mfma_f32_16x16x32_bf16 v[130:133], v[150:153], v[190:193], v[130:133]
	v_mfma_f32_16x16x32_bf16 v[126:129], v[158:161], v[190:193], v[126:129]
	v_mfma_f32_16x16x32_bf16 v[114:117], v[150:153], v[182:185], v[114:117]
	v_mfma_f32_16x16x32_bf16 v[110:113], v[158:161], v[182:185], v[110:113]
	v_mfma_f32_16x16x32_bf16 v[98:101], v[150:153], v[174:177], v[98:101]
	v_mfma_f32_16x16x32_bf16 v[94:97], v[158:161], v[174:177], v[94:97]
	v_mfma_f32_16x16x32_bf16 v[74:77], v[150:153], v[166:169], v[74:77]
	v_mfma_f32_16x16x32_bf16 v[62:65], v[158:161], v[166:169], v[62:65]
	v_mfma_f32_16x16x32_bf16 v[130:133], v[154:157], v[194:197], v[130:133]
	v_mfma_f32_16x16x32_bf16 v[126:129], v[162:165], v[194:197], v[126:129]
	v_mfma_f32_16x16x32_bf16 v[114:117], v[154:157], v[186:189], v[114:117]
	v_mfma_f32_16x16x32_bf16 v[110:113], v[162:165], v[186:189], v[110:113]
	v_mfma_f32_16x16x32_bf16 v[98:101], v[154:157], v[178:181], v[98:101]
	v_mfma_f32_16x16x32_bf16 v[94:97], v[162:165], v[178:181], v[94:97]
	v_mfma_f32_16x16x32_bf16 v[74:77], v[154:157], v[170:173], v[74:77]
	v_mfma_f32_16x16x32_bf16 v[62:65], v[162:165], v[170:173], v[62:65]
	s_setprio 0
	s_setprio 1
	v_mfma_f32_16x16x32_bf16 v[122:125], v[134:137], v[190:193], v[122:125]
	v_mfma_f32_16x16x32_bf16 v[118:121], v[142:145], v[190:193], v[118:121]
	v_mfma_f32_16x16x32_bf16 v[106:109], v[134:137], v[182:185], v[106:109]
	v_mfma_f32_16x16x32_bf16 v[102:105], v[142:145], v[182:185], v[102:105]
	v_mfma_f32_16x16x32_bf16 v[86:89], v[134:137], v[174:177], v[86:89]
	v_mfma_f32_16x16x32_bf16 v[78:81], v[142:145], v[174:177], v[78:81]
	v_mfma_f32_16x16x32_bf16 v[50:53], v[134:137], v[166:169], v[50:53]
	v_mfma_f32_16x16x32_bf16 v[34:37], v[142:145], v[166:169], v[34:37]
	v_mfma_f32_16x16x32_bf16 v[122:125], v[138:141], v[194:197], v[122:125]
	v_mfma_f32_16x16x32_bf16 v[118:121], v[146:149], v[194:197], v[118:121]
	v_mfma_f32_16x16x32_bf16 v[106:109], v[138:141], v[186:189], v[106:109]
	v_mfma_f32_16x16x32_bf16 v[102:105], v[146:149], v[186:189], v[102:105]
	v_mfma_f32_16x16x32_bf16 v[86:89], v[138:141], v[178:181], v[86:89]
	v_mfma_f32_16x16x32_bf16 v[78:81], v[146:149], v[178:181], v[78:81]
	v_mfma_f32_16x16x32_bf16 v[50:53], v[138:141], v[170:173], v[50:53]
	v_mfma_f32_16x16x32_bf16 v[34:37], v[146:149], v[170:173], v[34:37]
.Lskiphalf_12:
	s_setprio 0
	s_barrier
	s_add_i32 s62, 0, 0x18000
	v_add_u32_e32 v0, s62, v231
	s_add_i32 s63, 0, 0x1c000
	ds_read_b128 v[134:137], v0
	ds_read_b128 v[138:141], v0 offset:1024
	ds_read_b128 v[142:145], v0 offset:2048
	ds_read_b128 v[146:149], v0 offset:3072
	v_add_u32_e32 v0, s63, v231
	ds_read_b128 v[150:153], v0
	ds_read_b128 v[154:157], v0 offset:1024
	ds_read_b128 v[158:161], v0 offset:2048
	ds_read_b128 v[162:165], v0 offset:3072
	s_add_u32 s60, s60, 0xb0000
	s_addc_u32 s61, s61, 0
	s_mov_b32 m0, s74
	v_lshl_add_u64 v[236:237], s[60:61], 0, v[198:199]
	ds_read_b128 v[166:169], v234 offset:32768
	ds_read_b128 v[170:173], v234 offset:33792
	ds_read_b128 v[174:177], v234 offset:34816
	ds_read_b128 v[178:181], v234 offset:35840
	ds_read_b128 v[182:185], v234 offset:36864
	ds_read_b128 v[186:189], v234 offset:37888
	ds_read_b128 v[190:193], v234 offset:38912
	ds_read_b128 v[194:197], v234 offset:39936
	global_load_lds_dwordx4 v[236:237], off
	v_lshl_add_u64 v[236:237], s[60:61], 0, v[200:201]
	s_mov_b32 m0, s75
	s_nop 0
	global_load_lds_dwordx4 v[236:237], off
	s_waitcnt vmcnt(8)
	s_waitcnt lgkmcnt(0)
	s_barrier
	s_setprio 1
	s_waitcnt lgkmcnt(0)
	v_mfma_f32_16x16x32_bf16 v[90:93], v[134:137], v[166:169], v[90:93]
	v_mfma_f32_16x16x32_bf16 v[82:85], v[142:145], v[166:169], v[82:85]
	v_mfma_f32_16x16x32_bf16 v[66:69], v[134:137], v[174:177], v[66:69]
	v_mfma_f32_16x16x32_bf16 v[54:57], v[142:145], v[174:177], v[54:57]
	v_mfma_f32_16x16x32_bf16 v[42:45], v[134:137], v[182:185], v[42:45]
	v_mfma_f32_16x16x32_bf16 v[30:33], v[142:145], v[182:185], v[30:33]
	v_mfma_f32_16x16x32_bf16 v[22:25], v[134:137], v[190:193], v[22:25]
	v_mfma_f32_16x16x32_bf16 v[14:17], v[142:145], v[190:193], v[14:17]
	v_mfma_f32_16x16x32_bf16 v[90:93], v[138:141], v[170:173], v[90:93]
	v_mfma_f32_16x16x32_bf16 v[82:85], v[146:149], v[170:173], v[82:85]
	v_mfma_f32_16x16x32_bf16 v[66:69], v[138:141], v[178:181], v[66:69]
	v_mfma_f32_16x16x32_bf16 v[54:57], v[146:149], v[178:181], v[54:57]
	v_mfma_f32_16x16x32_bf16 v[42:45], v[138:141], v[186:189], v[42:45]
	v_mfma_f32_16x16x32_bf16 v[30:33], v[146:149], v[186:189], v[30:33]
	v_mfma_f32_16x16x32_bf16 v[22:25], v[138:141], v[194:197], v[22:25]
	v_mfma_f32_16x16x32_bf16 v[14:17], v[146:149], v[194:197], v[14:17]
	s_setprio 0
	s_setprio 1
	v_mfma_f32_16x16x32_bf16 v[70:73], v[150:153], v[166:169], v[70:73]
	v_mfma_f32_16x16x32_bf16 v[58:61], v[158:161], v[166:169], v[58:61]
	v_mfma_f32_16x16x32_bf16 v[46:49], v[150:153], v[174:177], v[46:49]
	v_mfma_f32_16x16x32_bf16 v[38:41], v[158:161], v[174:177], v[38:41]
	v_mfma_f32_16x16x32_bf16 v[26:29], v[150:153], v[182:185], v[26:29]
	v_mfma_f32_16x16x32_bf16 v[18:21], v[158:161], v[182:185], v[18:21]
	v_mfma_f32_16x16x32_bf16 v[10:13], v[150:153], v[190:193], v[10:13]
	v_mfma_f32_16x16x32_bf16 v[6:9], v[158:161], v[190:193], v[6:9]
	v_mfma_f32_16x16x32_bf16 v[70:73], v[154:157], v[170:173], v[70:73]
	v_mfma_f32_16x16x32_bf16 v[58:61], v[162:165], v[170:173], v[58:61]
	v_mfma_f32_16x16x32_bf16 v[46:49], v[154:157], v[178:181], v[46:49]
	v_mfma_f32_16x16x32_bf16 v[38:41], v[162:165], v[178:181], v[38:41]
	v_mfma_f32_16x16x32_bf16 v[26:29], v[154:157], v[186:189], v[26:29]
	v_mfma_f32_16x16x32_bf16 v[18:21], v[162:165], v[186:189], v[18:21]
	v_mfma_f32_16x16x32_bf16 v[10:13], v[154:157], v[194:197], v[10:13]
	v_mfma_f32_16x16x32_bf16 v[6:9], v[162:165], v[194:197], v[6:9]
	s_setprio 0
	s_barrier
; #define PG8_STAGE(bufoff, gbase, voff) do { _Pragma("unroll") for (int _i = 0; _i < 2; ++_i) \
;         __builtin_amdgcn_global_load_lds((const unsigned*)((const char*)(gbase) + (voff)[_i]), (PG8_LAS unsigned*)(lds + (bufoff) + ldsw + _i * 8192), 16, 0, 0); } while (0)
; #define PG8_LDA(dst, b, h) do { _Pragma("unroll") for (int m = 0; m < 4; ++m) _Pragma("unroll") for (int k = 0; k < 2; ++k) dst[m][k] = *(const PG8_LAS bf16x8*)(lds + PG8_SA(b, h) + aoff + m * 2048 + k * 1024); } while (0)
; #define PG8_MMA(ai, bj, At, Bt) do { __builtin_amdgcn_s_setprio(1); _Pragma("unroll") for (int m = 0; m < 4; ++m) _Pragma("unroll") for (int n = 0; n < 2; ++n) _Pragma("unroll") for (int k = 0; k < 2; ++k) \
;         acc[ai][bj][m][n] = __builtin_amdgcn_mfma_f32_16x16x32_bf16(Bt[n][k], At[m][k], acc[ai][bj][m][n], 0, 0, 0); __builtin_amdgcn_s_setprio(0); } while (0)
; #define PG8_WAIT_V(n) asm volatile("s_waitcnt vmcnt(" #n ")" ::: "memory")
; #define PG8_WAIT_L(n) asm volatile("s_waitcnt lgkmcnt(" #n ")" ::: "memory")
; #define PG8_BAR __builtin_amdgcn_s_barrier()
; #define PG8_SCHED __builtin_amdgcn_sched_barrier(0)
; template <class Epi, class Sched, bool ALIGN_EPI = false, bool SP2 = false, class Bg = BgNone>
; __device__ __forceinline__ void gemm_phase(PG8_LAS unsigned char* lds, const Gemm g, const Sched& S, const Epi& E, const int wave_sg, const Bg& bg = Bg()) {
;     ...
;             PG8_LDA(At, 1, 1); PG8_STAGE(PG8_SB(1, 0), b3, voffB); PG8_STAGE(PG8_SB(1, 1), b3 + hstep, voffB); PG8_STAGE(PG8_SA(1, 0), a3, voffA);
;             PG8_WAIT_V(8); PG8_WAIT_L(0); PG8_BAR; PG8_MMA(1, 0, At, B0); PG8_MMA(1, 1, At, B1); PG8_BAR; PG8_SCHED;
	s_add_i32 s60, s62, s67
	v_lshl_add_u64 v[228:229], v[228:229], 0, s[22:23]
	s_mov_b32 m0, s60
	ds_read_b128 v[166:169], v234 offset:49152
	ds_read_b128 v[170:173], v234 offset:50176
	ds_read_b128 v[174:177], v234 offset:51200
	ds_read_b128 v[178:181], v234 offset:52224
	ds_read_b128 v[182:185], v234 offset:53248
	ds_read_b128 v[186:189], v234 offset:54272
	ds_read_b128 v[190:193], v234 offset:55296
	ds_read_b128 v[194:197], v234 offset:56320
	global_load_lds_dwordx4 v[228:229], off
	s_add_i32 m0, s60, 0x2000
	s_add_u32 s58, s58, 0xb0080
	v_lshl_add_u64 v[226:227], v[226:227], 0, s[22:23]
	s_addc_u32 s59, s59, 0
	s_add_i32 s60, s63, s67
	global_load_lds_dwordx4 v[226:227], off
	v_lshl_add_u64 v[226:227], s[58:59], 0, v[198:199]
	s_mov_b32 m0, s60
	v_lshl_add_u64 v[222:223], v[222:223], 0, s[22:23]
	global_load_lds_dwordx4 v[226:227], off
	v_lshl_add_u64 v[226:227], s[58:59], 0, v[200:201]
	s_add_i32 m0, s60, 0x2000
	s_nop 0
	global_load_lds_dwordx4 v[226:227], off
	s_mov_b32 m0, s78
	s_nop 0
	global_load_lds_dwordx4 v[222:223], off
	v_lshl_add_u64 v[222:223], v[224:225], 0, s[22:23]
	s_mov_b32 m0, s79
	s_nop 0
	global_load_lds_dwordx4 v[222:223], off
	s_waitcnt vmcnt(8)
	s_waitcnt lgkmcnt(0)
	s_barrier
	s_setprio 1
	s_waitcnt lgkmcnt(0)
	s_cmpk_eq_u32 s93, 0x80
	s_cbranch_scc1 .Lskiphalf_13
	v_mfma_f32_16x16x32_bf16 v[130:133], v[134:137], v[166:169], v[130:133]
	v_mfma_f32_16x16x32_bf16 v[126:129], v[142:145], v[166:169], v[126:129]
	v_mfma_f32_16x16x32_bf16 v[114:117], v[134:137], v[174:177], v[114:117]
	v_mfma_f32_16x16x32_bf16 v[110:113], v[142:145], v[174:177], v[110:113]
	v_mfma_f32_16x16x32_bf16 v[98:101], v[134:137], v[182:185], v[98:101]
	v_mfma_f32_16x16x32_bf16 v[94:97], v[142:145], v[182:185], v[94:97]
	v_mfma_f32_16x16x32_bf16 v[74:77], v[134:137], v[190:193], v[74:77]
	v_mfma_f32_16x16x32_bf16 v[62:65], v[142:145], v[190:193], v[62:65]
	v_mfma_f32_16x16x32_bf16 v[130:133], v[138:141], v[170:173], v[130:133]
	v_mfma_f32_16x16x32_bf16 v[126:129], v[146:149], v[170:173], v[126:129]
	v_mfma_f32_16x16x32_bf16 v[114:117], v[138:141], v[178:181], v[114:117]
	v_mfma_f32_16x16x32_bf16 v[110:113], v[146:149], v[178:181], v[110:113]
	v_mfma_f32_16x16x32_bf16 v[98:101], v[138:141], v[186:189], v[98:101]
	v_mfma_f32_16x16x32_bf16 v[94:97], v[146:149], v[186:189], v[94:97]
	v_mfma_f32_16x16x32_bf16 v[74:77], v[138:141], v[194:197], v[74:77]
	v_mfma_f32_16x16x32_bf16 v[62:65], v[146:149], v[194:197], v[62:65]
	s_setprio 0
	s_setprio 1
	v_mfma_f32_16x16x32_bf16 v[122:125], v[150:153], v[166:169], v[122:125]
	v_mfma_f32_16x16x32_bf16 v[118:121], v[158:161], v[166:169], v[118:121]
	v_mfma_f32_16x16x32_bf16 v[106:109], v[150:153], v[174:177], v[106:109]
	v_mfma_f32_16x16x32_bf16 v[102:105], v[158:161], v[174:177], v[102:105]
	v_mfma_f32_16x16x32_bf16 v[86:89], v[150:153], v[182:185], v[86:89]
	v_mfma_f32_16x16x32_bf16 v[78:81], v[158:161], v[182:185], v[78:81]
	v_mfma_f32_16x16x32_bf16 v[50:53], v[150:153], v[190:193], v[50:53]
	v_mfma_f32_16x16x32_bf16 v[34:37], v[158:161], v[190:193], v[34:37]
	v_mfma_f32_16x16x32_bf16 v[122:125], v[154:157], v[170:173], v[122:125]
	v_mfma_f32_16x16x32_bf16 v[118:121], v[162:165], v[170:173], v[118:121]
	v_mfma_f32_16x16x32_bf16 v[106:109], v[154:157], v[178:181], v[106:109]
	v_mfma_f32_16x16x32_bf16 v[102:105], v[162:165], v[178:181], v[102:105]
	v_mfma_f32_16x16x32_bf16 v[86:89], v[154:157], v[186:189], v[86:89]
	v_mfma_f32_16x16x32_bf16 v[78:81], v[162:165], v[186:189], v[78:81]
	v_mfma_f32_16x16x32_bf16 v[50:53], v[154:157], v[194:197], v[50:53]
	v_mfma_f32_16x16x32_bf16 v[34:37], v[162:165], v[194:197], v[34:37]
.Lskiphalf_13:
	s_setprio 0
	s_barrier
	s_add_u32 s56, s56, 0x100
	s_addc_u32 s57, s57, 0
	s_cmp_ge_i32 s97, s49
	v_add_u32_e32 v235, s82, v235
	s_cbranch_scc1 .LBB0_1292
